# variant of v32: fourth K/V ds_write of each tile issued in PV group 2 instead of group 3 (shorter drain before the barrier)
# baseline (speedup 1.0000x reference)
; #define SBAR() __builtin_amdgcn_sched_barrier(0)
; __device__ __forceinline__ void finishSM(f32x16& p0, f32x16& p1, float alpha, float& l_reg, bf16x8& pa0, bf16x8& pa1, bf16x8& pa2, bf16x8& pa3) {
;   for (int r = 0; r < 16; ++r) p1[r] = __builtin_amdgcn_exp2f(p1[r]);
;   float ps = 0; for (int r = 0; r < 16; ++r) ps += p0[r]; for (int r = 0; r < 16; ++r) ps += p1[r];
;   { auto rr = __builtin_amdgcn_permlane32_swap(__float_as_uint(ps), __float_as_uint(ps), false, false);
;     ps = __uint_as_float(rr[0]) + __uint_as_float(rr[1]); }
;   l_reg = l_reg * alpha + ps;
;     ...
;   PK4(p0, 0, pa0); PK4(p0, 8, pa1); PK4(p1, 0, pa2); PK4(p1, 8, pa3);
;     ...
; }
; template <int BOFF> __device__ __forceinline__ void qkt_i(f32x16& p0, f32x16& p1, const int (&kb)[4], const bf16x8* qr) {
;   p0 = f32x16{}; p1 = f32x16{};
; #pragma unroll
;   for (int d0 = 0; d0 < 8; ++d0) { const int off = BOFF + (d0 >> 2) * 128;
;     const bf16x8 b0 = LDSV(kb[d0 & 3] + off), b1 = LDSV(kb[d0 & 3] + off + 8192);
;     p0 = __builtin_amdgcn_mfma_f32_32x32x16_bf16(b0, qr[d0], p0, 0, 0, 0);
;     p1 = __builtin_amdgcn_mfma_f32_32x32x16_bf16(b1, qr[d0], p1, 0, 0, 0); }
; }
; template <int D0, int BOFF> __device__ __forceinline__ void pv_one_i(f32x16& od, int vb, bf16x8 pa0, bf16x8 pa1, bf16x8 pa2, bf16x8 pa3) {
;   const s16x4 l0 = tr_read<BOFF + v_rd_off(D0, 0, 0)>(vb), h0 = tr_read<BOFF + v_rd_off(D0, 0, 1)>(vb), l1 = tr_read<BOFF + v_rd_off(D0, 1, 0)>(vb), h1 = tr_read<BOFF + v_rd_off(D0, 1, 1)>(vb);
;   const s16x4 l2 = tr_read<BOFF + v_rd_off(D0, 2, 0)>(vb), h2 = tr_read<BOFF + v_rd_off(D0, 2, 1)>(vb), l3 = tr_read<BOFF + v_rd_off(D0, 3, 0)>(vb), h3 = tr_read<BOFF + v_rd_off(D0, 3, 1)>(vb);
;   asm volatile("s_waitcnt lgkmcnt(0)" ::: "memory"); SBAR();
;     ...
;   od = __builtin_amdgcn_mfma_f32_32x32x16_bf16(pa0, PK(l0, h0), od, 0, 0, 0);
;   od = __builtin_amdgcn_mfma_f32_32x32x16_bf16(pa1, PK(l1, h1), od, 0, 0, 0);
;   od = __builtin_amdgcn_mfma_f32_32x32x16_bf16(pa2, PK(l2, h2), od, 0, 0, 0);
;   od = __builtin_amdgcn_mfma_f32_32x32x16_bf16(pa3, PK(l3, h3), od, 0, 0, 0);
;     ...
; }
; template <int BOFF> __device__ __forceinline__ void pv_i(f32x16* o, int vb, bf16x8 pa0, bf16x8 pa1, bf16x8 pa2, bf16x8 pa3) {
;   pv_one_i<0, BOFF>(o[0], vb, pa0, pa1, pa2, pa3); pv_one_i<1, BOFF>(o[1], vb, pa0, pa1, pa2, pa3); pv_one_i<2, BOFF>(o[2], vb, pa0, pa1, pa2, pa3); pv_one_i<3, BOFF>(o[3], vb, pa0, pa1, pa2, pa3);
; }
.LBB0_352:
	s_waitcnt lgkmcnt(0)
	s_barrier
	ds_read_b128 v[80:83], v207 offset:16384
	ds_read_b128 v[84:87], v207 offset:24576
	ds_read_b128 v[162:165], v208 offset:16384
	ds_read_b128 v[166:169], v208 offset:24576
	v_exp_f32_e32 v170, v72
	v_exp_f32_e32 v171, v73
	v_exp_f32_e32 v172, v74
	v_exp_f32_e32 v173, v75
	v_exp_f32_e32 v174, v76
	v_exp_f32_e32 v175, v77
	v_exp_f32_e32 v176, v78
	v_exp_f32_e32 v79, v79
	s_waitcnt lgkmcnt(3)
	v_mfma_f32_32x32x16_bf16 v[96:111], v[80:83], v[142:145], 0
	v_exp_f32_e32 v236, v64
	v_add_f32_e32 v64, 0, v229
	v_add_f32_e32 v64, v243, v64
	v_add_f32_e32 v64, v244, v64
	s_waitcnt lgkmcnt(2)
	v_mfma_f32_32x32x16_bf16 v[80:95], v[84:87], v[142:145], 0
	v_add_f32_e32 v64, v246, v64
	v_add_f32_e32 v64, v242, v64
	v_add_f32_e32 v64, v245, v64
	s_waitcnt lgkmcnt(1)
	v_mfma_f32_32x32x16_bf16 v[96:111], v[162:165], v[138:141], v[96:111]
	v_add_f32_e32 v64, v227, v64
	v_add_f32_e32 v64, v228, v64
	v_add_f32_e32 v64, v223, v64
	s_waitcnt lgkmcnt(0)
	v_mfma_f32_32x32x16_bf16 v[80:95], v[166:169], v[138:141], v[80:95]
	ds_read_b128 v[162:165], v209 offset:16384
	ds_read_b128 v[166:169], v209 offset:24576
	v_add_f32_e32 v64, v226, v64
	v_add_f32_e32 v64, v224, v64
	v_add_f32_e32 v64, v225, v64
	v_add_f32_e32 v64, v220, v64
	v_exp_f32_e32 v237, v65
	s_waitcnt lgkmcnt(1)
	v_mfma_f32_32x32x16_bf16 v[96:111], v[162:165], v[112:115], v[96:111]
	v_add_f32_e32 v64, v222, v64
	v_exp_f32_e32 v238, v66
	v_add_f32_e32 v64, v219, v64
	v_exp_f32_e32 v239, v67
	s_waitcnt lgkmcnt(0)
	v_mfma_f32_32x32x16_bf16 v[80:95], v[166:169], v[112:115], v[80:95]
	ds_read_b128 v[162:165], v210 offset:16384
	ds_read_b128 v[166:169], v210 offset:24576
	v_add_f32_e32 v64, v221, v64
	v_exp_f32_e32 v247, v68
	v_add_f32_e32 v64, v236, v64
	v_exp_f32_e32 v248, v69
	s_waitcnt lgkmcnt(1)
	v_mfma_f32_32x32x16_bf16 v[96:111], v[162:165], v[116:119], v[96:111]
	v_add_f32_e32 v64, v237, v64
	v_exp_f32_e32 v249, v70
	v_add_f32_e32 v64, v238, v64
	v_exp_f32_e32 v252, v71
	s_waitcnt lgkmcnt(0)
	v_mfma_f32_32x32x16_bf16 v[80:95], v[166:169], v[116:119], v[80:95]
	ds_read_b128 v[162:165], v190 offset:16384
	ds_read_b128 v[166:169], v190 offset:24576
	v_add_f32_e32 v64, v239, v64
	v_add_f32_e32 v64, v247, v64
	v_add_f32_e32 v64, v248, v64
	v_add_f32_e32 v64, v249, v64
	v_add_f32_e32 v64, v252, v64
	v_add_f32_e32 v64, v170, v64
	s_waitcnt lgkmcnt(1)
	v_mfma_f32_32x32x16_bf16 v[96:111], v[162:165], v[120:123], v[96:111]
	v_add_f32_e32 v64, v171, v64
	v_add_f32_e32 v64, v172, v64
	v_add_f32_e32 v64, v173, v64
	v_add_f32_e32 v64, v174, v64
	v_add_f32_e32 v64, v175, v64
	s_waitcnt lgkmcnt(0)
	v_mfma_f32_32x32x16_bf16 v[80:95], v[166:169], v[120:123], v[80:95]
	ds_read_b128 v[162:165], v191 offset:16384
	ds_read_b128 v[166:169], v191 offset:24576
	v_add_f32_e32 v64, v176, v64
	v_add_f32_e32 v64, v79, v64
	v_mov_b32_e32 v65, v64
	s_nop 1
	v_permlane32_swap_b32_e32 v64, v65
	v_add_f32_e32 v64, v64, v65
	s_waitcnt lgkmcnt(1)
	v_mfma_f32_32x32x16_bf16 v[96:111], v[162:165], v[124:127], v[96:111]
	v_add_f32_e32 v128, v215, v64
	v_cvt_pk_bf16_f32 v64, v229, v243
	v_cvt_pk_bf16_f32 v65, v244, v246
	v_cvt_pk_bf16_f32 v66, v242, v245
	v_cvt_pk_bf16_f32 v67, v227, v228
	s_waitcnt lgkmcnt(0)
	v_mfma_f32_32x32x16_bf16 v[80:95], v[166:169], v[124:127], v[80:95]
	ds_read_b128 v[162:165], v192 offset:16384
	ds_read_b128 v[166:169], v192 offset:24576
	v_cvt_pk_bf16_f32 v68, v223, v226
	v_cvt_pk_bf16_f32 v69, v224, v225
	v_cvt_pk_bf16_f32 v70, v220, v222
	v_cvt_pk_bf16_f32 v71, v219, v221
	v_cvt_pk_bf16_f32 v72, v236, v237
	v_cvt_pk_bf16_f32 v73, v238, v239
	s_waitcnt lgkmcnt(1)
	v_mfma_f32_32x32x16_bf16 v[96:111], v[162:165], v[130:133], v[96:111]
	v_cvt_pk_bf16_f32 v74, v247, v248
	v_cvt_pk_bf16_f32 v75, v249, v252
	v_cvt_pk_bf16_f32 v76, v170, v171
	v_cvt_pk_bf16_f32 v77, v172, v173
	v_cvt_pk_bf16_f32 v78, v174, v175
	s_waitcnt lgkmcnt(0)
	v_mfma_f32_32x32x16_bf16 v[80:95], v[166:169], v[130:133], v[80:95]
	ds_read_b128 v[162:165], v193 offset:16384
	ds_read_b128 v[166:169], v193 offset:24576
	ds_read_b64_tr_b16 v[180:181], v206 offset:0
	ds_read_b64_tr_b16 v[182:183], v206 offset:0x800
	ds_read_b64_tr_b16 v[184:185], v206 offset:0x1000
	ds_read_b64_tr_b16 v[186:187], v206 offset:0x1800
	ds_read_b64_tr_b16 v[216:217], v206 offset:0x2000
	ds_read_b64_tr_b16 v[218:219], v206 offset:0x2800
	ds_read_b64_tr_b16 v[220:221], v206 offset:0x3000
	ds_read_b64_tr_b16 v[222:223], v206 offset:0x3800
	v_cvt_pk_bf16_f32 v79, v176, v79
	s_nop 0
	v_permlane32_swap_b32_e32 v64, v66
	v_permlane32_swap_b32_e32 v65, v67
	v_permlane32_swap_b32_e32 v68, v70
	v_permlane32_swap_b32_e32 v69, v71
	s_waitcnt lgkmcnt(9)
	v_mfma_f32_32x32x16_bf16 v[96:111], v[162:165], v[134:137], v[96:111]
	v_permlane32_swap_b32_e32 v72, v74
	v_permlane32_swap_b32_e32 v73, v75
	v_permlane32_swap_b32_e32 v76, v78
	v_permlane32_swap_b32_e32 v77, v79
	s_waitcnt lgkmcnt(8)
	v_mfma_f32_32x32x16_bf16 v[80:95], v[166:169], v[134:137], v[80:95]
	s_waitcnt vmcnt(0)
	ds_write_b128 v211, v[146:149] offset:32768
	s_nop 0
	s_waitcnt lgkmcnt(7)
	v_mfma_f32_32x32x16_bf16 v[0:15], v[64:67], v[180:183], v[0:15]
	ds_read_b64_tr_b16 v[180:181], v206 offset:0x200
	ds_read_b64_tr_b16 v[182:183], v206 offset:0xa00
	v_add_co_u32_e32 v166, vcc, s19, v178
	s_nop 1
	v_addc_co_u32_e32 v167, vcc, -1, v179, vcc
	v_add_co_u32_e32 v170, vcc, s20, v178
	s_nop 1
	v_addc_co_u32_e32 v171, vcc, -1, v179, vcc
	s_waitcnt lgkmcnt(7)
	v_mfma_f32_32x32x16_bf16 v[0:15], v[68:71], v[184:187], v[0:15]
	ds_read_b64_tr_b16 v[184:185], v206 offset:0x1200
	ds_read_b64_tr_b16 v[186:187], v206 offset:0x1a00
	global_load_dwordx4 v[162:165], v[166:167], off
	s_nop 0
	global_load_dwordx4 v[166:169], v[166:167], off offset:-512
	s_nop 0
	global_load_dwordx4 v[174:177], v[170:171], off
	s_nop 0
	global_load_dwordx4 v[170:173], v[170:171], off offset:-512
	s_waitcnt lgkmcnt(7)
; #define SBAR() __builtin_amdgcn_sched_barrier(0)
; __device__ __forceinline__ void partialSM_fixed(f32x16& p0) {
;   for (int r = 0; r < 16; ++r) p0[r] = __builtin_amdgcn_exp2f(p0[r]);
; }
; __device__ __forceinline__ void finishSM(f32x16& p0, f32x16& p1, float alpha, float& l_reg, bf16x8& pa0, bf16x8& pa1, bf16x8& pa2, bf16x8& pa3) {
;   for (int r = 0; r < 16; ++r) p1[r] = __builtin_amdgcn_exp2f(p1[r]);
;   float ps = 0; for (int r = 0; r < 16; ++r) ps += p0[r]; for (int r = 0; r < 16; ++r) ps += p1[r];
;   { auto rr = __builtin_amdgcn_permlane32_swap(__float_as_uint(ps), __float_as_uint(ps), false, false);
;     ps = __uint_as_float(rr[0]) + __uint_as_float(rr[1]); }
;   l_reg = l_reg * alpha + ps;
;     ...
;   PK4(p0, 0, pa0); PK4(p0, 8, pa1); PK4(p1, 0, pa2); PK4(p1, 8, pa3);
;     ...
; }
; template <int D0, int BOFF> __device__ __forceinline__ void pv_one_i(f32x16& od, int vb, bf16x8 pa0, bf16x8 pa1, bf16x8 pa2, bf16x8 pa3) {
;   const s16x4 l0 = tr_read<BOFF + v_rd_off(D0, 0, 0)>(vb), h0 = tr_read<BOFF + v_rd_off(D0, 0, 1)>(vb), l1 = tr_read<BOFF + v_rd_off(D0, 1, 0)>(vb), h1 = tr_read<BOFF + v_rd_off(D0, 1, 1)>(vb);
;   const s16x4 l2 = tr_read<BOFF + v_rd_off(D0, 2, 0)>(vb), h2 = tr_read<BOFF + v_rd_off(D0, 2, 1)>(vb), l3 = tr_read<BOFF + v_rd_off(D0, 3, 0)>(vb), h3 = tr_read<BOFF + v_rd_off(D0, 3, 1)>(vb);
;   asm volatile("s_waitcnt lgkmcnt(0)" ::: "memory"); SBAR();
;     ...
;   od = __builtin_amdgcn_mfma_f32_32x32x16_bf16(pa0, PK(l0, h0), od, 0, 0, 0);
;   od = __builtin_amdgcn_mfma_f32_32x32x16_bf16(pa1, PK(l1, h1), od, 0, 0, 0);
;   od = __builtin_amdgcn_mfma_f32_32x32x16_bf16(pa2, PK(l2, h2), od, 0, 0, 0);
;   od = __builtin_amdgcn_mfma_f32_32x32x16_bf16(pa3, PK(l3, h3), od, 0, 0, 0);
;     ...
; }
; template <int BOFF> __device__ __forceinline__ void pv_i(f32x16* o, int vb, bf16x8 pa0, bf16x8 pa1, bf16x8 pa2, bf16x8 pa3) {
;   pv_one_i<0, BOFF>(o[0], vb, pa0, pa1, pa2, pa3); pv_one_i<1, BOFF>(o[1], vb, pa0, pa1, pa2, pa3); pv_one_i<2, BOFF>(o[2], vb, pa0, pa1, pa2, pa3); pv_one_i<3, BOFF>(o[3], vb, pa0, pa1, pa2, pa3);
; }
	v_mfma_f32_32x32x16_bf16 v[0:15], v[72:75], v[216:219], v[0:15]
	ds_read_b64_tr_b16 v[216:217], v206 offset:0x2200
	ds_read_b64_tr_b16 v[218:219], v206 offset:0x2a00
	s_waitcnt lgkmcnt(7)
	v_mfma_f32_32x32x16_bf16 v[0:15], v[76:79], v[220:223], v[0:15]
	ds_read_b64_tr_b16 v[220:221], v206 offset:0x3200
	ds_read_b64_tr_b16 v[222:223], v206 offset:0x3a00
	ds_write_b128 v212, v[150:153] offset:32768
	s_waitcnt lgkmcnt(7)
	v_mfma_f32_32x32x16_bf16 v[16:31], v[64:67], v[180:183], v[16:31]
	ds_read_b64_tr_b16 v[180:181], v206 offset:0x400
	ds_read_b64_tr_b16 v[182:183], v206 offset:0xc00
	s_waitcnt lgkmcnt(7)
	v_mfma_f32_32x32x16_bf16 v[16:31], v[68:71], v[184:187], v[16:31]
	ds_read_b64_tr_b16 v[184:185], v206 offset:0x1400
	ds_read_b64_tr_b16 v[186:187], v206 offset:0x1c00
	s_waitcnt lgkmcnt(7)
	v_mfma_f32_32x32x16_bf16 v[16:31], v[72:75], v[216:219], v[16:31]
	ds_read_b64_tr_b16 v[216:217], v206 offset:0x2400
	ds_read_b64_tr_b16 v[218:219], v206 offset:0x2c00
	s_waitcnt lgkmcnt(7)
	v_mfma_f32_32x32x16_bf16 v[16:31], v[76:79], v[220:223], v[16:31]
	ds_read_b64_tr_b16 v[220:221], v206 offset:0x3400
	ds_read_b64_tr_b16 v[222:223], v206 offset:0x3c00
	ds_write_b128 v213, v[154:157] offset:32768
	s_waitcnt lgkmcnt(7)
	v_mfma_f32_32x32x16_bf16 v[32:47], v[64:67], v[180:183], v[32:47]
	ds_read_b64_tr_b16 v[180:181], v206 offset:0x600
	ds_read_b64_tr_b16 v[182:183], v206 offset:0xe00
	v_exp_f32_e32 v215, v108
	v_exp_f32_e32 v188, v102
	s_waitcnt lgkmcnt(7)
	v_mfma_f32_32x32x16_bf16 v[32:47], v[68:71], v[184:187], v[32:47]
	ds_read_b64_tr_b16 v[184:185], v206 offset:0x1600
	ds_read_b64_tr_b16 v[186:187], v206 offset:0x1e00
	v_exp_f32_e32 v189, v103
	v_exp_f32_e32 v196, v104
	ds_write_b128 v214, v[158:161] offset:32768
	s_waitcnt lgkmcnt(8)
	v_mfma_f32_32x32x16_bf16 v[32:47], v[72:75], v[216:219], v[32:47]
	ds_read_b64_tr_b16 v[216:217], v206 offset:0x2600
	ds_read_b64_tr_b16 v[218:219], v206 offset:0x2e00
	v_exp_f32_e32 v197, v105
	v_exp_f32_e32 v198, v106
	s_waitcnt lgkmcnt(8)
	v_mfma_f32_32x32x16_bf16 v[32:47], v[76:79], v[220:223], v[32:47]
	ds_read_b64_tr_b16 v[220:221], v206 offset:0x3600
	ds_read_b64_tr_b16 v[222:223], v206 offset:0x3e00
	v_exp_f32_e32 v199, v107
	s_waitcnt lgkmcnt(7)
	v_mfma_f32_32x32x16_bf16 v[48:63], v[64:67], v[180:183], v[48:63]
	s_waitcnt vmcnt(4)
	v_exp_f32_e32 v181, v96
	v_exp_f32_e32 v183, v97
	s_waitcnt lgkmcnt(5)
	v_mfma_f32_32x32x16_bf16 v[48:63], v[68:71], v[184:187], v[48:63]
	v_exp_f32_e32 v184, v98
	v_exp_f32_e32 v185, v99
	v_exp_f32_e32 v186, v100
	v_exp_f32_e32 v187, v101
	s_waitcnt lgkmcnt(2)
	v_mfma_f32_32x32x16_bf16 v[48:63], v[72:75], v[216:219], v[48:63]
	v_exp_f32_e32 v216, v109
	v_exp_f32_e32 v217, v110
	v_exp_f32_e32 v218, v111
	s_waitcnt lgkmcnt(0)
	s_barrier
	v_mfma_f32_32x32x16_bf16 v[48:63], v[76:79], v[220:223], v[48:63]
	ds_read_b128 v[64:67], v207 offset:32768
	ds_read_b128 v[96:99], v207 offset:40960
	ds_read_b128 v[146:149], v208 offset:32768
	ds_read_b128 v[150:153], v208 offset:40960
	v_exp_f32_e32 v154, v88
	v_exp_f32_e32 v155, v89
	v_exp_f32_e32 v156, v90
	v_exp_f32_e32 v157, v91
	v_exp_f32_e32 v158, v92
	v_exp_f32_e32 v159, v93
	v_exp_f32_e32 v160, v94
	v_exp_f32_e32 v95, v95
	s_waitcnt lgkmcnt(3)
	v_mfma_f32_32x32x16_bf16 v[64:79], v[64:67], v[142:145], 0
	v_exp_f32_e32 v236, v80
	v_add_f32_e32 v80, 0, v181
	v_add_f32_e32 v80, v183, v80
	v_add_f32_e32 v80, v184, v80
	s_waitcnt lgkmcnt(2)
	v_mfma_f32_32x32x16_bf16 v[96:111], v[96:99], v[142:145], 0
	v_add_f32_e32 v80, v185, v80
	v_add_f32_e32 v80, v186, v80
	v_add_f32_e32 v80, v187, v80
	s_waitcnt lgkmcnt(1)
	v_mfma_f32_32x32x16_bf16 v[64:79], v[146:149], v[138:141], v[64:79]
	v_add_f32_e32 v80, v188, v80
	v_add_f32_e32 v80, v189, v80
	v_add_f32_e32 v80, v196, v80
	s_waitcnt lgkmcnt(0)
	v_mfma_f32_32x32x16_bf16 v[96:111], v[150:153], v[138:141], v[96:111]
	ds_read_b128 v[146:149], v209 offset:32768
	ds_read_b128 v[150:153], v209 offset:40960
	v_add_f32_e32 v80, v197, v80
	v_add_f32_e32 v80, v198, v80
	v_add_f32_e32 v80, v199, v80
	v_add_f32_e32 v80, v215, v80
	v_exp_f32_e32 v237, v81
	s_waitcnt lgkmcnt(1)
	v_mfma_f32_32x32x16_bf16 v[64:79], v[146:149], v[112:115], v[64:79]
	v_add_f32_e32 v80, v216, v80
	v_exp_f32_e32 v238, v82
	v_add_f32_e32 v80, v217, v80
	v_exp_f32_e32 v239, v83
	s_waitcnt lgkmcnt(0)
	v_mfma_f32_32x32x16_bf16 v[96:111], v[150:153], v[112:115], v[96:111]
	ds_read_b128 v[146:149], v210 offset:32768
	ds_read_b128 v[150:153], v210 offset:40960
	v_add_f32_e32 v80, v218, v80
	v_exp_f32_e32 v247, v84
	v_add_f32_e32 v80, v236, v80
	v_exp_f32_e32 v248, v85
	s_waitcnt lgkmcnt(1)
	v_mfma_f32_32x32x16_bf16 v[64:79], v[146:149], v[116:119], v[64:79]
	v_add_f32_e32 v80, v237, v80
	v_exp_f32_e32 v249, v86
	v_add_f32_e32 v80, v238, v80
	v_exp_f32_e32 v252, v87
	s_waitcnt lgkmcnt(0)
	v_mfma_f32_32x32x16_bf16 v[96:111], v[150:153], v[116:119], v[96:111]
	ds_read_b128 v[146:149], v190 offset:32768
	ds_read_b128 v[150:153], v190 offset:40960
	v_add_f32_e32 v80, v239, v80
	v_add_f32_e32 v80, v247, v80
	v_add_f32_e32 v80, v248, v80
	v_add_f32_e32 v80, v249, v80
	v_add_f32_e32 v80, v252, v80
	v_add_f32_e32 v80, v154, v80
	s_waitcnt lgkmcnt(1)
	v_mfma_f32_32x32x16_bf16 v[64:79], v[146:149], v[120:123], v[64:79]
	v_add_f32_e32 v80, v155, v80
	v_add_f32_e32 v80, v156, v80
	v_add_f32_e32 v80, v157, v80
	v_add_f32_e32 v80, v158, v80
	v_add_f32_e32 v80, v159, v80
	s_waitcnt lgkmcnt(0)
	v_mfma_f32_32x32x16_bf16 v[96:111], v[150:153], v[120:123], v[96:111]
	ds_read_b128 v[146:149], v191 offset:32768
	ds_read_b128 v[150:153], v191 offset:40960
	v_add_f32_e32 v80, v160, v80
	v_add_f32_e32 v180, v95, v80
	v_mov_b32_e32 v182, v180
	v_cvt_pk_bf16_f32 v80, v181, v183
	v_cvt_pk_bf16_f32 v81, v184, v185
	v_cvt_pk_bf16_f32 v82, v186, v187
	s_waitcnt lgkmcnt(1)
; #define SBAR() __builtin_amdgcn_sched_barrier(0)
; __device__ __forceinline__ void partialSM_fixed(f32x16& p0) {
;   for (int r = 0; r < 16; ++r) p0[r] = __builtin_amdgcn_exp2f(p0[r]);
; }
; __device__ __forceinline__ void finishSM(f32x16& p0, f32x16& p1, float alpha, float& l_reg, bf16x8& pa0, bf16x8& pa1, bf16x8& pa2, bf16x8& pa3) {
;   for (int r = 0; r < 16; ++r) p1[r] = __builtin_amdgcn_exp2f(p1[r]);
;   float ps = 0; for (int r = 0; r < 16; ++r) ps += p0[r]; for (int r = 0; r < 16; ++r) ps += p1[r];
;   { auto rr = __builtin_amdgcn_permlane32_swap(__float_as_uint(ps), __float_as_uint(ps), false, false);
;     ps = __uint_as_float(rr[0]) + __uint_as_float(rr[1]); }
;   l_reg = l_reg * alpha + ps;
;     ...
;   PK4(p0, 0, pa0); PK4(p0, 8, pa1); PK4(p1, 0, pa2); PK4(p1, 8, pa3);
;     ...
; }
; template <int D0, int BOFF> __device__ __forceinline__ void pv_one_i(f32x16& od, int vb, bf16x8 pa0, bf16x8 pa1, bf16x8 pa2, bf16x8 pa3) {
;   const s16x4 l0 = tr_read<BOFF + v_rd_off(D0, 0, 0)>(vb), h0 = tr_read<BOFF + v_rd_off(D0, 0, 1)>(vb), l1 = tr_read<BOFF + v_rd_off(D0, 1, 0)>(vb), h1 = tr_read<BOFF + v_rd_off(D0, 1, 1)>(vb);
;   const s16x4 l2 = tr_read<BOFF + v_rd_off(D0, 2, 0)>(vb), h2 = tr_read<BOFF + v_rd_off(D0, 2, 1)>(vb), l3 = tr_read<BOFF + v_rd_off(D0, 3, 0)>(vb), h3 = tr_read<BOFF + v_rd_off(D0, 3, 1)>(vb);
;   asm volatile("s_waitcnt lgkmcnt(0)" ::: "memory"); SBAR();
;     ...
;   od = __builtin_amdgcn_mfma_f32_32x32x16_bf16(pa0, PK(l0, h0), od, 0, 0, 0);
;   od = __builtin_amdgcn_mfma_f32_32x32x16_bf16(pa1, PK(l1, h1), od, 0, 0, 0);
;   od = __builtin_amdgcn_mfma_f32_32x32x16_bf16(pa2, PK(l2, h2), od, 0, 0, 0);
;   od = __builtin_amdgcn_mfma_f32_32x32x16_bf16(pa3, PK(l3, h3), od, 0, 0, 0);
;     ...
; }
; template <int BOFF> __device__ __forceinline__ void pv_i(f32x16* o, int vb, bf16x8 pa0, bf16x8 pa1, bf16x8 pa2, bf16x8 pa3) {
;   pv_one_i<0, BOFF>(o[0], vb, pa0, pa1, pa2, pa3); pv_one_i<1, BOFF>(o[1], vb, pa0, pa1, pa2, pa3); pv_one_i<2, BOFF>(o[2], vb, pa0, pa1, pa2, pa3); pv_one_i<3, BOFF>(o[3], vb, pa0, pa1, pa2, pa3);
; }
	v_mfma_f32_32x32x16_bf16 v[64:79], v[146:149], v[124:127], v[64:79]
	v_cvt_pk_bf16_f32 v83, v188, v189
	v_cvt_pk_bf16_f32 v84, v196, v197
	v_cvt_pk_bf16_f32 v85, v198, v199
	v_cvt_pk_bf16_f32 v86, v215, v216
	v_cvt_pk_bf16_f32 v87, v217, v218
	s_waitcnt lgkmcnt(0)
	v_mfma_f32_32x32x16_bf16 v[96:111], v[150:153], v[124:127], v[96:111]
	ds_read_b128 v[146:149], v192 offset:32768
	ds_read_b128 v[150:153], v192 offset:40960
	v_cvt_pk_bf16_f32 v88, v236, v237
	v_cvt_pk_bf16_f32 v89, v238, v239
	v_cvt_pk_bf16_f32 v90, v247, v248
	v_cvt_pk_bf16_f32 v91, v249, v252
	v_cvt_pk_bf16_f32 v92, v154, v155
	v_cvt_pk_bf16_f32 v93, v156, v157
	s_waitcnt lgkmcnt(1)
	v_mfma_f32_32x32x16_bf16 v[64:79], v[146:149], v[130:133], v[64:79]
	v_cvt_pk_bf16_f32 v94, v158, v159
	v_cvt_pk_bf16_f32 v95, v160, v95
	s_nop 1
	v_permlane32_swap_b32_e32 v180, v182
	v_permlane32_swap_b32_e32 v80, v82
	s_waitcnt lgkmcnt(0)
	v_mfma_f32_32x32x16_bf16 v[96:111], v[150:153], v[130:133], v[96:111]
	ds_read_b128 v[146:149], v193 offset:32768
	ds_read_b128 v[150:153], v193 offset:40960
	ds_read_b64_tr_b16 v[184:185], v206 offset:0x4000
	ds_read_b64_tr_b16 v[186:187], v206 offset:0x4800
	ds_read_b64_tr_b16 v[216:217], v206 offset:0x5000
	ds_read_b64_tr_b16 v[218:219], v206 offset:0x5800
	ds_read_b64_tr_b16 v[220:221], v206 offset:0x6000
	ds_read_b64_tr_b16 v[222:223], v206 offset:0x6800
	ds_read_b64_tr_b16 v[224:225], v206 offset:0x7000
	ds_read_b64_tr_b16 v[226:227], v206 offset:0x7800
	v_permlane32_swap_b32_e32 v81, v83
	v_permlane32_swap_b32_e32 v84, v86
	v_permlane32_swap_b32_e32 v85, v87
	v_permlane32_swap_b32_e32 v88, v90
	v_permlane32_swap_b32_e32 v89, v91
	v_permlane32_swap_b32_e32 v92, v94
	s_waitcnt lgkmcnt(9)
	v_mfma_f32_32x32x16_bf16 v[64:79], v[146:149], v[134:137], v[64:79]
	v_permlane32_swap_b32_e32 v93, v95
	s_waitcnt lgkmcnt(8)
	v_mfma_f32_32x32x16_bf16 v[96:111], v[150:153], v[134:137], v[96:111]
	s_waitcnt vmcnt(0)
	ds_write_b128 v211, v[162:165]
	s_nop 0
	s_waitcnt lgkmcnt(7)
	v_mfma_f32_32x32x16_bf16 v[0:15], v[80:83], v[184:187], v[0:15]
	ds_read_b64_tr_b16 v[184:185], v206 offset:0x4200
	ds_read_b64_tr_b16 v[186:187], v206 offset:0x4a00
	v_add_co_u32_e32 v150, vcc, s21, v178
	s_nop 1
	v_addc_co_u32_e32 v151, vcc, -1, v179, vcc
	v_add_co_u32_e32 v154, vcc, s22, v178
	s_nop 1
	v_addc_co_u32_e32 v155, vcc, -1, v179, vcc
	s_waitcnt lgkmcnt(7)
	v_mfma_f32_32x32x16_bf16 v[0:15], v[84:87], v[216:219], v[0:15]
	ds_read_b64_tr_b16 v[216:217], v206 offset:0x5200
	ds_read_b64_tr_b16 v[218:219], v206 offset:0x5a00
	global_load_dwordx4 v[146:149], v[150:151], off
	s_nop 0
	global_load_dwordx4 v[150:153], v[150:151], off offset:-512
	s_nop 0
	global_load_dwordx4 v[158:161], v[154:155], off
	s_nop 0
	global_load_dwordx4 v[154:157], v[154:155], off offset:-512
	s_waitcnt lgkmcnt(7)
	v_mfma_f32_32x32x16_bf16 v[0:15], v[88:91], v[220:223], v[0:15]
	ds_read_b64_tr_b16 v[220:221], v206 offset:0x6200
	ds_read_b64_tr_b16 v[222:223], v206 offset:0x6a00
	s_waitcnt lgkmcnt(7)
	v_mfma_f32_32x32x16_bf16 v[0:15], v[92:95], v[224:227], v[0:15]
	ds_read_b64_tr_b16 v[224:225], v206 offset:0x7200
	ds_read_b64_tr_b16 v[226:227], v206 offset:0x7a00
	ds_write_b128 v212, v[174:177]
	s_waitcnt lgkmcnt(7)
	v_mfma_f32_32x32x16_bf16 v[16:31], v[80:83], v[184:187], v[16:31]
	ds_read_b64_tr_b16 v[184:185], v206 offset:0x4400
	ds_read_b64_tr_b16 v[186:187], v206 offset:0x4c00
	s_waitcnt lgkmcnt(7)
	v_mfma_f32_32x32x16_bf16 v[16:31], v[84:87], v[216:219], v[16:31]
	ds_read_b64_tr_b16 v[216:217], v206 offset:0x5400
	ds_read_b64_tr_b16 v[218:219], v206 offset:0x5c00
	s_waitcnt lgkmcnt(7)
	v_mfma_f32_32x32x16_bf16 v[16:31], v[88:91], v[220:223], v[16:31]
	ds_read_b64_tr_b16 v[220:221], v206 offset:0x6400
	ds_read_b64_tr_b16 v[222:223], v206 offset:0x6c00
	s_waitcnt lgkmcnt(7)
	v_mfma_f32_32x32x16_bf16 v[16:31], v[92:95], v[224:227], v[16:31]
	ds_read_b64_tr_b16 v[224:225], v206 offset:0x7400
	ds_read_b64_tr_b16 v[226:227], v206 offset:0x7c00
	ds_write_b128 v213, v[166:169]
	s_waitcnt lgkmcnt(7)
	v_mfma_f32_32x32x16_bf16 v[32:47], v[80:83], v[184:187], v[32:47]
	ds_read_b64_tr_b16 v[184:185], v206 offset:0x4600
	ds_read_b64_tr_b16 v[186:187], v206 offset:0x4e00
	v_exp_f32_e32 v215, v74
	v_exp_f32_e32 v188, v68
	s_waitcnt lgkmcnt(7)
	v_mfma_f32_32x32x16_bf16 v[32:47], v[84:87], v[216:219], v[32:47]
	ds_read_b64_tr_b16 v[216:217], v206 offset:0x5600
	ds_read_b64_tr_b16 v[218:219], v206 offset:0x5e00
	v_exp_f32_e32 v189, v69
	v_exp_f32_e32 v196, v70
	ds_write_b128 v214, v[170:173]
	s_waitcnt lgkmcnt(8)
	v_mfma_f32_32x32x16_bf16 v[32:47], v[88:91], v[220:223], v[32:47]
	ds_read_b64_tr_b16 v[220:221], v206 offset:0x6600
	ds_read_b64_tr_b16 v[222:223], v206 offset:0x6e00
	v_exp_f32_e32 v197, v71
	v_exp_f32_e32 v198, v72
	s_waitcnt lgkmcnt(8)
	v_mfma_f32_32x32x16_bf16 v[32:47], v[92:95], v[224:227], v[32:47]
	ds_read_b64_tr_b16 v[224:225], v206 offset:0x7600
	ds_read_b64_tr_b16 v[226:227], v206 offset:0x7e00
	v_exp_f32_e32 v199, v73
	s_waitcnt lgkmcnt(7)
	v_mfma_f32_32x32x16_bf16 v[48:63], v[80:83], v[184:187], v[48:63]
	s_waitcnt vmcnt(4)
	v_exp_f32_e32 v184, v64
	v_exp_f32_e32 v185, v65
	v_exp_f32_e32 v186, v66
	v_exp_f32_e32 v187, v67
	s_waitcnt lgkmcnt(5)
	v_mfma_f32_32x32x16_bf16 v[48:63], v[84:87], v[216:219], v[48:63]
	v_exp_f32_e32 v219, v78
	v_exp_f32_e32 v216, v75
	s_waitcnt lgkmcnt(2)
	v_mfma_f32_32x32x16_bf16 v[48:63], v[88:91], v[220:223], v[48:63]
	v_exp_f32_e32 v220, v79
	v_exp_f32_e32 v217, v76
	v_exp_f32_e32 v218, v77
	s_waitcnt lgkmcnt(0)
	s_barrier
; __device__ __forceinline__ void finishSM(f32x16& p0, f32x16& p1, float alpha, float& l_reg, bf16x8& pa0, bf16x8& pa1, bf16x8& pa2, bf16x8& pa3) {
;   for (int r = 0; r < 16; ++r) p1[r] = __builtin_amdgcn_exp2f(p1[r]);
;   float ps = 0; for (int r = 0; r < 16; ++r) ps += p0[r]; for (int r = 0; r < 16; ++r) ps += p1[r];
;   { auto rr = __builtin_amdgcn_permlane32_swap(__float_as_uint(ps), __float_as_uint(ps), false, false);
;     ps = __uint_as_float(rr[0]) + __uint_as_float(rr[1]); }
;   l_reg = l_reg * alpha + ps;
;     ...
;   PK4(p0, 0, pa0); PK4(p0, 8, pa1); PK4(p1, 0, pa2); PK4(p1, 8, pa3);
;     ...
; }
; template <int BOFF> __device__ __forceinline__ void qkt_i(f32x16& p0, f32x16& p1, const int (&kb)[4], const bf16x8* qr) {
;   p0 = f32x16{}; p1 = f32x16{};
; #pragma unroll
;   for (int d0 = 0; d0 < 8; ++d0) { const int off = BOFF + (d0 >> 2) * 128;
;     const bf16x8 b0 = LDSV(kb[d0 & 3] + off), b1 = LDSV(kb[d0 & 3] + off + 8192);
;     p0 = __builtin_amdgcn_mfma_f32_32x32x16_bf16(b0, qr[d0], p0, 0, 0, 0);
;     p1 = __builtin_amdgcn_mfma_f32_32x32x16_bf16(b1, qr[d0], p1, 0, 0, 0); }
; }
	v_mfma_f32_32x32x16_bf16 v[48:63], v[92:95], v[224:227], v[48:63]
	ds_read_b128 v[64:67], v207
	ds_read_b128 v[68:71], v207 offset:8192
	ds_read_b128 v[162:165], v208
	ds_read_b128 v[166:169], v208 offset:8192
	v_exp_f32_e32 v170, v104
	v_exp_f32_e32 v171, v105
	v_exp_f32_e32 v172, v106
	v_exp_f32_e32 v173, v107
	v_exp_f32_e32 v174, v108
	v_exp_f32_e32 v175, v109
	v_exp_f32_e32 v176, v110
	v_exp_f32_e32 v111, v111
	s_waitcnt lgkmcnt(3)
	v_mfma_f32_32x32x16_bf16 v[80:95], v[64:67], v[142:145], 0
	v_exp_f32_e32 v236, v96
	v_add_f32_e32 v96, 0, v184
	v_add_f32_e32 v96, v185, v96
	v_add_f32_e32 v96, v186, v96
	s_waitcnt lgkmcnt(2)
	v_mfma_f32_32x32x16_bf16 v[64:79], v[68:71], v[142:145], 0
	v_add_f32_e32 v96, v187, v96
	v_add_f32_e32 v96, v188, v96
	v_add_f32_e32 v96, v189, v96
	s_waitcnt lgkmcnt(1)
	v_mfma_f32_32x32x16_bf16 v[80:95], v[162:165], v[138:141], v[80:95]
	v_add_f32_e32 v96, v196, v96
	v_add_f32_e32 v96, v197, v96
	v_add_f32_e32 v96, v198, v96
	s_waitcnt lgkmcnt(0)
	v_mfma_f32_32x32x16_bf16 v[64:79], v[166:169], v[138:141], v[64:79]
	ds_read_b128 v[162:165], v209
	ds_read_b128 v[166:169], v209 offset:8192
	v_add_f32_e32 v96, v199, v96
	v_add_f32_e32 v96, v215, v96
	v_add_f32_e32 v96, v216, v96
	v_add_f32_e32 v96, v217, v96
	v_exp_f32_e32 v237, v97
	s_waitcnt lgkmcnt(1)
	v_mfma_f32_32x32x16_bf16 v[80:95], v[162:165], v[112:115], v[80:95]
	v_add_f32_e32 v96, v218, v96
	v_exp_f32_e32 v238, v98
	v_add_f32_e32 v96, v219, v96
	v_exp_f32_e32 v239, v99
	s_waitcnt lgkmcnt(0)
	v_mfma_f32_32x32x16_bf16 v[64:79], v[166:169], v[112:115], v[64:79]
	ds_read_b128 v[162:165], v210
	ds_read_b128 v[166:169], v210 offset:8192
	v_add_f32_e32 v96, v220, v96
	v_exp_f32_e32 v247, v100
	v_add_f32_e32 v96, v236, v96
	v_exp_f32_e32 v248, v101
	s_waitcnt lgkmcnt(1)
	v_mfma_f32_32x32x16_bf16 v[80:95], v[162:165], v[116:119], v[80:95]
	v_add_f32_e32 v96, v237, v96
	v_exp_f32_e32 v249, v102
	v_add_f32_e32 v96, v238, v96
	v_exp_f32_e32 v252, v103
	s_waitcnt lgkmcnt(0)
	v_mfma_f32_32x32x16_bf16 v[64:79], v[166:169], v[116:119], v[64:79]
	ds_read_b128 v[162:165], v190 offset:0
	ds_read_b128 v[166:169], v190 offset:8192
	v_add_f32_e32 v96, v239, v96
	v_add_f32_e32 v96, v247, v96
	v_add_f32_e32 v96, v248, v96
	v_add_f32_e32 v96, v249, v96
	v_add_f32_e32 v96, v252, v96
	v_add_f32_e32 v96, v170, v96
	s_waitcnt lgkmcnt(1)
	v_mfma_f32_32x32x16_bf16 v[80:95], v[162:165], v[120:123], v[80:95]
	v_add_f32_e32 v96, v171, v96
	v_add_f32_e32 v96, v172, v96
	v_add_f32_e32 v96, v173, v96
	v_add_f32_e32 v96, v174, v96
	v_add_f32_e32 v96, v175, v96
	s_waitcnt lgkmcnt(0)
	v_mfma_f32_32x32x16_bf16 v[64:79], v[166:169], v[120:123], v[64:79]
	ds_read_b128 v[162:165], v191 offset:0
	ds_read_b128 v[166:169], v191 offset:8192
	v_add_f32_e32 v96, v176, v96
	v_add_f32_e32 v181, v111, v96
	v_mov_b32_e32 v183, v181
	s_nop 1
	v_permlane32_swap_b32_e32 v181, v183
	v_pk_add_f32 v[96:97], v[180:181], v[182:183]
	s_waitcnt lgkmcnt(1)
	v_mfma_f32_32x32x16_bf16 v[80:95], v[162:165], v[124:127], v[80:95]
	s_nop 0
	v_add_f32_e32 v96, v128, v96
	v_add_f32_e32 v128, v96, v97
	v_cvt_pk_bf16_f32 v96, v184, v185
	v_cvt_pk_bf16_f32 v97, v186, v187
	s_waitcnt lgkmcnt(0)
	v_mfma_f32_32x32x16_bf16 v[64:79], v[166:169], v[124:127], v[64:79]
	ds_read_b128 v[162:165], v192 offset:0
	ds_read_b128 v[166:169], v192 offset:8192
	v_cvt_pk_bf16_f32 v98, v188, v189
	v_cvt_pk_bf16_f32 v99, v196, v197
	v_cvt_pk_bf16_f32 v100, v198, v199
	v_cvt_pk_bf16_f32 v101, v215, v216
	v_cvt_pk_bf16_f32 v102, v217, v218
	v_cvt_pk_bf16_f32 v103, v219, v220
	s_waitcnt lgkmcnt(1)
	v_mfma_f32_32x32x16_bf16 v[80:95], v[162:165], v[130:133], v[80:95]
	v_cvt_pk_bf16_f32 v104, v236, v237
	v_cvt_pk_bf16_f32 v105, v238, v239
	v_cvt_pk_bf16_f32 v106, v247, v248
	v_cvt_pk_bf16_f32 v107, v249, v252
	v_cvt_pk_bf16_f32 v108, v170, v171
	s_waitcnt lgkmcnt(0)
	v_mfma_f32_32x32x16_bf16 v[64:79], v[166:169], v[130:133], v[64:79]
	ds_read_b128 v[162:165], v193 offset:0
	ds_read_b128 v[166:169], v193 offset:8192
	ds_read_b64_tr_b16 v[180:181], v206 offset:0x8000
	ds_read_b64_tr_b16 v[182:183], v206 offset:0x8800
	ds_read_b64_tr_b16 v[184:185], v206 offset:0x9000
	ds_read_b64_tr_b16 v[186:187], v206 offset:0x9800
	ds_read_b64_tr_b16 v[216:217], v206 offset:0xa000
	ds_read_b64_tr_b16 v[218:219], v206 offset:0xa800
	ds_read_b64_tr_b16 v[220:221], v206 offset:0xb000
	ds_read_b64_tr_b16 v[222:223], v206 offset:0xb800
	v_cvt_pk_bf16_f32 v109, v172, v173
	v_cvt_pk_bf16_f32 v110, v174, v175
	v_cvt_pk_bf16_f32 v111, v176, v111
	s_nop 0
	v_permlane32_swap_b32_e32 v96, v98
	v_permlane32_swap_b32_e32 v97, v99
	s_waitcnt lgkmcnt(9)
	v_mfma_f32_32x32x16_bf16 v[80:95], v[162:165], v[134:137], v[80:95]
	v_permlane32_swap_b32_e32 v100, v102
	v_permlane32_swap_b32_e32 v101, v103
	v_permlane32_swap_b32_e32 v104, v106
	v_permlane32_swap_b32_e32 v105, v107
	v_permlane32_swap_b32_e32 v108, v110
	s_waitcnt lgkmcnt(8)
	v_mfma_f32_32x32x16_bf16 v[64:79], v[166:169], v[134:137], v[64:79]
	v_permlane32_swap_b32_e32 v109, v111
	s_waitcnt vmcnt(0)
	ds_write_b128 v211, v[146:149] offset:16384
	s_nop 0
	s_waitcnt lgkmcnt(7)
	v_mfma_f32_32x32x16_bf16 v[0:15], v[96:99], v[180:183], v[0:15]
	ds_read_b64_tr_b16 v[180:181], v206 offset:0x8200
	ds_read_b64_tr_b16 v[182:183], v206 offset:0x8a00
	v_add_co_u32_e32 v166, vcc, s23, v178
	s_nop 1
	v_addc_co_u32_e32 v167, vcc, -1, v179, vcc
	v_add_co_u32_e32 v170, vcc, s24, v178
	s_nop 1
	v_addc_co_u32_e32 v171, vcc, -1, v179, vcc
	s_waitcnt lgkmcnt(7)
; #define SBAR() __builtin_amdgcn_sched_barrier(0)
; __device__ __forceinline__ void partialSM_fixed(f32x16& p0) {
;   for (int r = 0; r < 16; ++r) p0[r] = __builtin_amdgcn_exp2f(p0[r]);
; }
; __device__ __forceinline__ void finishSM(f32x16& p0, f32x16& p1, float alpha, float& l_reg, bf16x8& pa0, bf16x8& pa1, bf16x8& pa2, bf16x8& pa3) {
;   for (int r = 0; r < 16; ++r) p1[r] = __builtin_amdgcn_exp2f(p1[r]);
;   float ps = 0; for (int r = 0; r < 16; ++r) ps += p0[r]; for (int r = 0; r < 16; ++r) ps += p1[r];
;   { auto rr = __builtin_amdgcn_permlane32_swap(__float_as_uint(ps), __float_as_uint(ps), false, false);
;     ps = __uint_as_float(rr[0]) + __uint_as_float(rr[1]); }
;   l_reg = l_reg * alpha + ps;
;     ...
;   PK4(p0, 0, pa0); PK4(p0, 8, pa1); PK4(p1, 0, pa2); PK4(p1, 8, pa3);
;     ...
; }
; template <int D0, int BOFF> __device__ __forceinline__ void pv_one_i(f32x16& od, int vb, bf16x8 pa0, bf16x8 pa1, bf16x8 pa2, bf16x8 pa3) {
;   const s16x4 l0 = tr_read<BOFF + v_rd_off(D0, 0, 0)>(vb), h0 = tr_read<BOFF + v_rd_off(D0, 0, 1)>(vb), l1 = tr_read<BOFF + v_rd_off(D0, 1, 0)>(vb), h1 = tr_read<BOFF + v_rd_off(D0, 1, 1)>(vb);
;   const s16x4 l2 = tr_read<BOFF + v_rd_off(D0, 2, 0)>(vb), h2 = tr_read<BOFF + v_rd_off(D0, 2, 1)>(vb), l3 = tr_read<BOFF + v_rd_off(D0, 3, 0)>(vb), h3 = tr_read<BOFF + v_rd_off(D0, 3, 1)>(vb);
;   asm volatile("s_waitcnt lgkmcnt(0)" ::: "memory"); SBAR();
;     ...
;   od = __builtin_amdgcn_mfma_f32_32x32x16_bf16(pa0, PK(l0, h0), od, 0, 0, 0);
;   od = __builtin_amdgcn_mfma_f32_32x32x16_bf16(pa1, PK(l1, h1), od, 0, 0, 0);
;   od = __builtin_amdgcn_mfma_f32_32x32x16_bf16(pa2, PK(l2, h2), od, 0, 0, 0);
;   od = __builtin_amdgcn_mfma_f32_32x32x16_bf16(pa3, PK(l3, h3), od, 0, 0, 0);
;     ...
; }
; template <int BOFF> __device__ __forceinline__ void pv_i(f32x16* o, int vb, bf16x8 pa0, bf16x8 pa1, bf16x8 pa2, bf16x8 pa3) {
;   pv_one_i<0, BOFF>(o[0], vb, pa0, pa1, pa2, pa3); pv_one_i<1, BOFF>(o[1], vb, pa0, pa1, pa2, pa3); pv_one_i<2, BOFF>(o[2], vb, pa0, pa1, pa2, pa3); pv_one_i<3, BOFF>(o[3], vb, pa0, pa1, pa2, pa3);
; }
	v_mfma_f32_32x32x16_bf16 v[0:15], v[100:103], v[184:187], v[0:15]
	ds_read_b64_tr_b16 v[184:185], v206 offset:0x9200
	ds_read_b64_tr_b16 v[186:187], v206 offset:0x9a00
	global_load_dwordx4 v[162:165], v[166:167], off
	s_nop 0
	global_load_dwordx4 v[166:169], v[166:167], off offset:-512
	s_nop 0
	global_load_dwordx4 v[174:177], v[170:171], off
	s_nop 0
	global_load_dwordx4 v[170:173], v[170:171], off offset:-512
	s_waitcnt lgkmcnt(7)
	v_mfma_f32_32x32x16_bf16 v[0:15], v[104:107], v[216:219], v[0:15]
	ds_read_b64_tr_b16 v[216:217], v206 offset:0xa200
	ds_read_b64_tr_b16 v[218:219], v206 offset:0xaa00
	s_waitcnt lgkmcnt(7)
	v_mfma_f32_32x32x16_bf16 v[0:15], v[108:111], v[220:223], v[0:15]
	ds_read_b64_tr_b16 v[220:221], v206 offset:0xb200
	ds_read_b64_tr_b16 v[222:223], v206 offset:0xba00
	ds_write_b128 v212, v[158:161] offset:16384
	s_waitcnt lgkmcnt(7)
	v_mfma_f32_32x32x16_bf16 v[16:31], v[96:99], v[180:183], v[16:31]
	ds_read_b64_tr_b16 v[180:181], v206 offset:0x8400
	ds_read_b64_tr_b16 v[182:183], v206 offset:0x8c00
	s_waitcnt lgkmcnt(7)
	v_mfma_f32_32x32x16_bf16 v[16:31], v[100:103], v[184:187], v[16:31]
	ds_read_b64_tr_b16 v[184:185], v206 offset:0x9400
	ds_read_b64_tr_b16 v[186:187], v206 offset:0x9c00
	s_waitcnt lgkmcnt(7)
	v_mfma_f32_32x32x16_bf16 v[16:31], v[104:107], v[216:219], v[16:31]
	ds_read_b64_tr_b16 v[216:217], v206 offset:0xa400
	ds_read_b64_tr_b16 v[218:219], v206 offset:0xac00
	s_waitcnt lgkmcnt(7)
	v_mfma_f32_32x32x16_bf16 v[16:31], v[108:111], v[220:223], v[16:31]
	ds_read_b64_tr_b16 v[220:221], v206 offset:0xb400
	ds_read_b64_tr_b16 v[222:223], v206 offset:0xbc00
	ds_write_b128 v213, v[150:153] offset:16384
	s_waitcnt lgkmcnt(7)
	v_mfma_f32_32x32x16_bf16 v[32:47], v[96:99], v[180:183], v[32:47]
	ds_read_b64_tr_b16 v[180:181], v206 offset:0x8600
	ds_read_b64_tr_b16 v[182:183], v206 offset:0x8e00
	v_exp_f32_e32 v215, v92
	v_exp_f32_e32 v188, v86
	s_waitcnt lgkmcnt(7)
	v_mfma_f32_32x32x16_bf16 v[32:47], v[100:103], v[184:187], v[32:47]
	ds_read_b64_tr_b16 v[184:185], v206 offset:0x9600
	ds_read_b64_tr_b16 v[186:187], v206 offset:0x9e00
	v_exp_f32_e32 v189, v87
	v_exp_f32_e32 v196, v88
	ds_write_b128 v214, v[154:157] offset:16384
	s_waitcnt lgkmcnt(8)
	v_mfma_f32_32x32x16_bf16 v[32:47], v[104:107], v[216:219], v[32:47]
	ds_read_b64_tr_b16 v[216:217], v206 offset:0xa600
	ds_read_b64_tr_b16 v[218:219], v206 offset:0xae00
	v_exp_f32_e32 v197, v89
	v_exp_f32_e32 v198, v90
	s_waitcnt lgkmcnt(8)
	v_mfma_f32_32x32x16_bf16 v[32:47], v[108:111], v[220:223], v[32:47]
	ds_read_b64_tr_b16 v[220:221], v206 offset:0xb600
	ds_read_b64_tr_b16 v[222:223], v206 offset:0xbe00
	v_exp_f32_e32 v199, v91
	s_waitcnt lgkmcnt(7)
	v_mfma_f32_32x32x16_bf16 v[48:63], v[96:99], v[180:183], v[48:63]
	s_waitcnt vmcnt(4)
	v_exp_f32_e32 v181, v80
	v_exp_f32_e32 v183, v81
	s_waitcnt lgkmcnt(5)
	v_mfma_f32_32x32x16_bf16 v[48:63], v[100:103], v[184:187], v[48:63]
	v_exp_f32_e32 v184, v82
	v_exp_f32_e32 v185, v83
	v_exp_f32_e32 v186, v84
	v_exp_f32_e32 v187, v85
	s_waitcnt lgkmcnt(2)
	v_mfma_f32_32x32x16_bf16 v[48:63], v[104:107], v[216:219], v[48:63]
	v_exp_f32_e32 v216, v93
	v_exp_f32_e32 v217, v94
	v_exp_f32_e32 v218, v95
	s_waitcnt lgkmcnt(0)
	s_barrier
	v_mfma_f32_32x32x16_bf16 v[48:63], v[108:111], v[220:223], v[48:63]
	ds_read_b128 v[80:83], v207 offset:16384
	ds_read_b128 v[96:99], v207 offset:24576
	ds_read_b128 v[146:149], v208 offset:16384
	ds_read_b128 v[150:153], v208 offset:24576
	v_exp_f32_e32 v154, v72
	v_exp_f32_e32 v155, v73
	v_exp_f32_e32 v156, v74
	v_exp_f32_e32 v157, v75
	v_exp_f32_e32 v158, v76
	v_exp_f32_e32 v159, v77
	v_exp_f32_e32 v160, v78
	v_exp_f32_e32 v79, v79
	s_waitcnt lgkmcnt(3)
	v_mfma_f32_32x32x16_bf16 v[80:95], v[80:83], v[142:145], 0
	v_exp_f32_e32 v236, v64
	v_add_f32_e32 v64, 0, v181
	v_add_f32_e32 v64, v183, v64
	v_add_f32_e32 v64, v184, v64
	s_waitcnt lgkmcnt(2)
	v_mfma_f32_32x32x16_bf16 v[96:111], v[96:99], v[142:145], 0
	v_add_f32_e32 v64, v185, v64
	v_add_f32_e32 v64, v186, v64
	v_add_f32_e32 v64, v187, v64
	s_waitcnt lgkmcnt(1)
	v_mfma_f32_32x32x16_bf16 v[80:95], v[146:149], v[138:141], v[80:95]
	v_add_f32_e32 v64, v188, v64
	v_add_f32_e32 v64, v189, v64
	v_add_f32_e32 v64, v196, v64
	s_waitcnt lgkmcnt(0)
	v_mfma_f32_32x32x16_bf16 v[96:111], v[150:153], v[138:141], v[96:111]
	ds_read_b128 v[146:149], v209 offset:16384
	ds_read_b128 v[150:153], v209 offset:24576
	v_add_f32_e32 v64, v197, v64
	v_add_f32_e32 v64, v198, v64
	v_add_f32_e32 v64, v199, v64
	v_add_f32_e32 v64, v215, v64
	v_exp_f32_e32 v237, v65
	s_waitcnt lgkmcnt(1)
	v_mfma_f32_32x32x16_bf16 v[80:95], v[146:149], v[112:115], v[80:95]
	v_add_f32_e32 v64, v216, v64
	v_exp_f32_e32 v238, v66
	v_add_f32_e32 v64, v217, v64
	v_exp_f32_e32 v239, v67
	s_waitcnt lgkmcnt(0)
	v_mfma_f32_32x32x16_bf16 v[96:111], v[150:153], v[112:115], v[96:111]
	ds_read_b128 v[146:149], v210 offset:16384
	ds_read_b128 v[150:153], v210 offset:24576
	v_add_f32_e32 v64, v218, v64
	v_exp_f32_e32 v247, v68
	v_add_f32_e32 v64, v236, v64
	v_exp_f32_e32 v248, v69
	s_waitcnt lgkmcnt(1)
	v_mfma_f32_32x32x16_bf16 v[80:95], v[146:149], v[116:119], v[80:95]
	v_add_f32_e32 v64, v237, v64
	v_exp_f32_e32 v249, v70
	v_add_f32_e32 v64, v238, v64
	v_exp_f32_e32 v252, v71
	s_waitcnt lgkmcnt(0)
	v_mfma_f32_32x32x16_bf16 v[96:111], v[150:153], v[116:119], v[96:111]
	ds_read_b128 v[146:149], v190 offset:16384
	ds_read_b128 v[150:153], v190 offset:24576
	v_add_f32_e32 v64, v239, v64
	v_add_f32_e32 v64, v247, v64
	v_add_f32_e32 v64, v248, v64
	v_add_f32_e32 v64, v249, v64
	v_add_f32_e32 v64, v252, v64
	v_add_f32_e32 v64, v154, v64
	s_waitcnt lgkmcnt(1)
; #define SBAR() __builtin_amdgcn_sched_barrier(0)
; __device__ __forceinline__ void partialSM_fixed(f32x16& p0) {
;   for (int r = 0; r < 16; ++r) p0[r] = __builtin_amdgcn_exp2f(p0[r]);
; }
; __device__ __forceinline__ void finishSM(f32x16& p0, f32x16& p1, float alpha, float& l_reg, bf16x8& pa0, bf16x8& pa1, bf16x8& pa2, bf16x8& pa3) {
;   for (int r = 0; r < 16; ++r) p1[r] = __builtin_amdgcn_exp2f(p1[r]);
;   float ps = 0; for (int r = 0; r < 16; ++r) ps += p0[r]; for (int r = 0; r < 16; ++r) ps += p1[r];
;   { auto rr = __builtin_amdgcn_permlane32_swap(__float_as_uint(ps), __float_as_uint(ps), false, false);
;     ps = __uint_as_float(rr[0]) + __uint_as_float(rr[1]); }
;   l_reg = l_reg * alpha + ps;
;     ...
;   PK4(p0, 0, pa0); PK4(p0, 8, pa1); PK4(p1, 0, pa2); PK4(p1, 8, pa3);
;     ...
; }
; template <int D0, int BOFF> __device__ __forceinline__ void pv_one_i(f32x16& od, int vb, bf16x8 pa0, bf16x8 pa1, bf16x8 pa2, bf16x8 pa3) {
;   const s16x4 l0 = tr_read<BOFF + v_rd_off(D0, 0, 0)>(vb), h0 = tr_read<BOFF + v_rd_off(D0, 0, 1)>(vb), l1 = tr_read<BOFF + v_rd_off(D0, 1, 0)>(vb), h1 = tr_read<BOFF + v_rd_off(D0, 1, 1)>(vb);
;   const s16x4 l2 = tr_read<BOFF + v_rd_off(D0, 2, 0)>(vb), h2 = tr_read<BOFF + v_rd_off(D0, 2, 1)>(vb), l3 = tr_read<BOFF + v_rd_off(D0, 3, 0)>(vb), h3 = tr_read<BOFF + v_rd_off(D0, 3, 1)>(vb);
;   asm volatile("s_waitcnt lgkmcnt(0)" ::: "memory"); SBAR();
;     ...
;   od = __builtin_amdgcn_mfma_f32_32x32x16_bf16(pa0, PK(l0, h0), od, 0, 0, 0);
;   od = __builtin_amdgcn_mfma_f32_32x32x16_bf16(pa1, PK(l1, h1), od, 0, 0, 0);
;   od = __builtin_amdgcn_mfma_f32_32x32x16_bf16(pa2, PK(l2, h2), od, 0, 0, 0);
;   od = __builtin_amdgcn_mfma_f32_32x32x16_bf16(pa3, PK(l3, h3), od, 0, 0, 0);
;     ...
; }
; template <int BOFF> __device__ __forceinline__ void pv_i(f32x16* o, int vb, bf16x8 pa0, bf16x8 pa1, bf16x8 pa2, bf16x8 pa3) {
;   pv_one_i<0, BOFF>(o[0], vb, pa0, pa1, pa2, pa3); pv_one_i<1, BOFF>(o[1], vb, pa0, pa1, pa2, pa3); pv_one_i<2, BOFF>(o[2], vb, pa0, pa1, pa2, pa3); pv_one_i<3, BOFF>(o[3], vb, pa0, pa1, pa2, pa3);
; }
	v_mfma_f32_32x32x16_bf16 v[80:95], v[146:149], v[120:123], v[80:95]
	v_add_f32_e32 v64, v155, v64
	v_add_f32_e32 v64, v156, v64
	v_add_f32_e32 v64, v157, v64
	v_add_f32_e32 v64, v158, v64
	v_add_f32_e32 v64, v159, v64
	s_waitcnt lgkmcnt(0)
	v_mfma_f32_32x32x16_bf16 v[96:111], v[150:153], v[120:123], v[96:111]
	ds_read_b128 v[146:149], v191 offset:16384
	ds_read_b128 v[150:153], v191 offset:24576
	v_add_f32_e32 v64, v160, v64
	v_add_f32_e32 v180, v79, v64
	v_cvt_pk_bf16_f32 v64, v181, v183
	v_cvt_pk_bf16_f32 v65, v184, v185
	v_cvt_pk_bf16_f32 v66, v186, v187
	v_cvt_pk_bf16_f32 v67, v188, v189
	s_waitcnt lgkmcnt(1)
	v_mfma_f32_32x32x16_bf16 v[80:95], v[146:149], v[124:127], v[80:95]
	v_cvt_pk_bf16_f32 v68, v196, v197
	v_cvt_pk_bf16_f32 v69, v198, v199
	v_cvt_pk_bf16_f32 v70, v215, v216
	v_cvt_pk_bf16_f32 v71, v217, v218
	v_cvt_pk_bf16_f32 v72, v236, v237
	s_waitcnt lgkmcnt(0)
	v_mfma_f32_32x32x16_bf16 v[96:111], v[150:153], v[124:127], v[96:111]
	ds_read_b128 v[146:149], v192 offset:16384
	ds_read_b128 v[150:153], v192 offset:24576
	v_cvt_pk_bf16_f32 v73, v238, v239
	v_cvt_pk_bf16_f32 v74, v247, v248
	v_cvt_pk_bf16_f32 v75, v249, v252
	v_cvt_pk_bf16_f32 v76, v154, v155
	v_cvt_pk_bf16_f32 v77, v156, v157
	v_cvt_pk_bf16_f32 v78, v158, v159
	s_waitcnt lgkmcnt(1)
	v_mfma_f32_32x32x16_bf16 v[80:95], v[146:149], v[130:133], v[80:95]
	v_cvt_pk_bf16_f32 v79, v160, v79
	v_mov_b32_e32 v182, v180
	v_permlane32_swap_b32_e32 v64, v66
	v_permlane32_swap_b32_e32 v65, v67
	v_permlane32_swap_b32_e32 v68, v70
	s_waitcnt lgkmcnt(0)
	v_mfma_f32_32x32x16_bf16 v[96:111], v[150:153], v[130:133], v[96:111]
	ds_read_b128 v[146:149], v193 offset:16384
	ds_read_b128 v[150:153], v193 offset:24576
	ds_read_b64_tr_b16 v[184:185], v206 offset:0
	ds_read_b64_tr_b16 v[186:187], v206 offset:0x800
	ds_read_b64_tr_b16 v[216:217], v206 offset:0x1000
	ds_read_b64_tr_b16 v[218:219], v206 offset:0x1800
	ds_read_b64_tr_b16 v[220:221], v206 offset:0x2000
	ds_read_b64_tr_b16 v[222:223], v206 offset:0x2800
	ds_read_b64_tr_b16 v[224:225], v206 offset:0x3000
	ds_read_b64_tr_b16 v[226:227], v206 offset:0x3800
	v_permlane32_swap_b32_e32 v69, v71
	v_permlane32_swap_b32_e32 v72, v74
	v_permlane32_swap_b32_e32 v73, v75
	v_permlane32_swap_b32_e32 v76, v78
	v_permlane32_swap_b32_e32 v77, v79
	v_permlane32_swap_b32_e32 v180, v182
	s_waitcnt lgkmcnt(9)
	v_mfma_f32_32x32x16_bf16 v[80:95], v[146:149], v[134:137], v[80:95]
	s_waitcnt lgkmcnt(8)
	v_mfma_f32_32x32x16_bf16 v[96:111], v[150:153], v[134:137], v[96:111]
	s_waitcnt vmcnt(0)
	ds_write_b128 v211, v[162:165] offset:32768
	s_nop 0
	s_waitcnt lgkmcnt(7)
	v_mfma_f32_32x32x16_bf16 v[0:15], v[64:67], v[184:187], v[0:15]
	ds_read_b64_tr_b16 v[184:185], v206 offset:0x200
	ds_read_b64_tr_b16 v[186:187], v206 offset:0xa00
	v_add_co_u32_e32 v150, vcc, s25, v178
	s_nop 1
	v_addc_co_u32_e32 v151, vcc, -1, v179, vcc
	v_add_co_u32_e32 v154, vcc, s45, v178
	s_nop 1
	v_addc_co_u32_e32 v155, vcc, -1, v179, vcc
	s_waitcnt lgkmcnt(7)
	v_mfma_f32_32x32x16_bf16 v[0:15], v[68:71], v[216:219], v[0:15]
	ds_read_b64_tr_b16 v[216:217], v206 offset:0x1200
	ds_read_b64_tr_b16 v[218:219], v206 offset:0x1a00
	global_load_dwordx4 v[146:149], v[150:151], off
	s_nop 0
	global_load_dwordx4 v[150:153], v[150:151], off offset:-512
	s_nop 0
	global_load_dwordx4 v[158:161], v[154:155], off
	s_nop 0
	global_load_dwordx4 v[154:157], v[154:155], off offset:-512
	s_waitcnt lgkmcnt(7)
	v_mfma_f32_32x32x16_bf16 v[0:15], v[72:75], v[220:223], v[0:15]
	ds_read_b64_tr_b16 v[220:221], v206 offset:0x2200
	ds_read_b64_tr_b16 v[222:223], v206 offset:0x2a00
	s_waitcnt lgkmcnt(7)
	v_mfma_f32_32x32x16_bf16 v[0:15], v[76:79], v[224:227], v[0:15]
	ds_read_b64_tr_b16 v[224:225], v206 offset:0x3200
	ds_read_b64_tr_b16 v[226:227], v206 offset:0x3a00
	ds_write_b128 v212, v[174:177] offset:32768
	s_waitcnt lgkmcnt(7)
	v_mfma_f32_32x32x16_bf16 v[16:31], v[64:67], v[184:187], v[16:31]
	ds_read_b64_tr_b16 v[184:185], v206 offset:0x400
	ds_read_b64_tr_b16 v[186:187], v206 offset:0xc00
	s_waitcnt lgkmcnt(7)
	v_mfma_f32_32x32x16_bf16 v[16:31], v[68:71], v[216:219], v[16:31]
	ds_read_b64_tr_b16 v[216:217], v206 offset:0x1400
	ds_read_b64_tr_b16 v[218:219], v206 offset:0x1c00
	s_waitcnt lgkmcnt(7)
	v_mfma_f32_32x32x16_bf16 v[16:31], v[72:75], v[220:223], v[16:31]
	ds_read_b64_tr_b16 v[220:221], v206 offset:0x2400
	ds_read_b64_tr_b16 v[222:223], v206 offset:0x2c00
	s_waitcnt lgkmcnt(7)
	v_mfma_f32_32x32x16_bf16 v[16:31], v[76:79], v[224:227], v[16:31]
	ds_read_b64_tr_b16 v[224:225], v206 offset:0x3400
	ds_read_b64_tr_b16 v[226:227], v206 offset:0x3c00
	ds_write_b128 v213, v[166:169] offset:32768
	s_waitcnt lgkmcnt(7)
	v_mfma_f32_32x32x16_bf16 v[32:47], v[64:67], v[184:187], v[32:47]
	ds_read_b64_tr_b16 v[184:185], v206 offset:0x600
	ds_read_b64_tr_b16 v[186:187], v206 offset:0xe00
	v_exp_f32_e32 v215, v90
	v_exp_f32_e32 v188, v84
	s_waitcnt lgkmcnt(7)
	v_mfma_f32_32x32x16_bf16 v[32:47], v[68:71], v[216:219], v[32:47]
	ds_read_b64_tr_b16 v[216:217], v206 offset:0x1600
	ds_read_b64_tr_b16 v[218:219], v206 offset:0x1e00
	v_exp_f32_e32 v189, v85
	v_exp_f32_e32 v196, v86
	ds_write_b128 v214, v[170:173] offset:32768
	s_waitcnt lgkmcnt(8)
	v_mfma_f32_32x32x16_bf16 v[32:47], v[72:75], v[220:223], v[32:47]
	ds_read_b64_tr_b16 v[220:221], v206 offset:0x2600
	ds_read_b64_tr_b16 v[222:223], v206 offset:0x2e00
	v_exp_f32_e32 v197, v87
	v_exp_f32_e32 v198, v88
	s_waitcnt lgkmcnt(8)
	v_mfma_f32_32x32x16_bf16 v[32:47], v[76:79], v[224:227], v[32:47]
	ds_read_b64_tr_b16 v[224:225], v206 offset:0x3600
	ds_read_b64_tr_b16 v[226:227], v206 offset:0x3e00
	v_exp_f32_e32 v199, v89
	s_waitcnt lgkmcnt(7)
	v_mfma_f32_32x32x16_bf16 v[48:63], v[64:67], v[184:187], v[48:63]
	s_waitcnt vmcnt(4)
	v_exp_f32_e32 v184, v80
	v_exp_f32_e32 v185, v81
	v_exp_f32_e32 v186, v82
	v_exp_f32_e32 v187, v83
	s_waitcnt lgkmcnt(5)
	v_mfma_f32_32x32x16_bf16 v[48:63], v[68:71], v[216:219], v[48:63]
	v_exp_f32_e32 v219, v94
	v_exp_f32_e32 v216, v91
	s_waitcnt lgkmcnt(2)
	v_mfma_f32_32x32x16_bf16 v[48:63], v[72:75], v[220:223], v[48:63]
	v_exp_f32_e32 v220, v95
	v_exp_f32_e32 v217, v92
	v_exp_f32_e32 v218, v93
	s_waitcnt lgkmcnt(0)
	s_barrier
; __device__ __forceinline__ void finishSM(f32x16& p0, f32x16& p1, float alpha, float& l_reg, bf16x8& pa0, bf16x8& pa1, bf16x8& pa2, bf16x8& pa3) {
;   for (int r = 0; r < 16; ++r) p1[r] = __builtin_amdgcn_exp2f(p1[r]);
;   float ps = 0; for (int r = 0; r < 16; ++r) ps += p0[r]; for (int r = 0; r < 16; ++r) ps += p1[r];
;   { auto rr = __builtin_amdgcn_permlane32_swap(__float_as_uint(ps), __float_as_uint(ps), false, false);
;     ps = __uint_as_float(rr[0]) + __uint_as_float(rr[1]); }
;   l_reg = l_reg * alpha + ps;
;     ...
;   PK4(p0, 0, pa0); PK4(p0, 8, pa1); PK4(p1, 0, pa2); PK4(p1, 8, pa3);
;     ...
; }
; template <int BOFF> __device__ __forceinline__ void qkt_i(f32x16& p0, f32x16& p1, const int (&kb)[4], const bf16x8* qr) {
;   p0 = f32x16{}; p1 = f32x16{};
; #pragma unroll
;   for (int d0 = 0; d0 < 8; ++d0) { const int off = BOFF + (d0 >> 2) * 128;
;     const bf16x8 b0 = LDSV(kb[d0 & 3] + off), b1 = LDSV(kb[d0 & 3] + off + 8192);
;     p0 = __builtin_amdgcn_mfma_f32_32x32x16_bf16(b0, qr[d0], p0, 0, 0, 0);
;     p1 = __builtin_amdgcn_mfma_f32_32x32x16_bf16(b1, qr[d0], p1, 0, 0, 0); }
; }
	v_mfma_f32_32x32x16_bf16 v[48:63], v[76:79], v[224:227], v[48:63]
	ds_read_b128 v[64:67], v207 offset:32768
	ds_read_b128 v[80:83], v207 offset:40960
	ds_read_b128 v[162:165], v208 offset:32768
	ds_read_b128 v[166:169], v208 offset:40960
	v_exp_f32_e32 v170, v104
	v_exp_f32_e32 v171, v105
	v_exp_f32_e32 v172, v106
	v_exp_f32_e32 v173, v107
	v_exp_f32_e32 v174, v108
	v_exp_f32_e32 v175, v109
	v_exp_f32_e32 v176, v110
	v_exp_f32_e32 v111, v111
	s_waitcnt lgkmcnt(3)
	v_mfma_f32_32x32x16_bf16 v[64:79], v[64:67], v[142:145], 0
	v_exp_f32_e32 v236, v96
	v_add_f32_e32 v96, 0, v184
	v_add_f32_e32 v96, v185, v96
	v_add_f32_e32 v96, v186, v96
	s_waitcnt lgkmcnt(2)
	v_mfma_f32_32x32x16_bf16 v[80:95], v[80:83], v[142:145], 0
	v_add_f32_e32 v96, v187, v96
	v_add_f32_e32 v96, v188, v96
	v_add_f32_e32 v96, v189, v96
	s_waitcnt lgkmcnt(1)
	v_mfma_f32_32x32x16_bf16 v[64:79], v[162:165], v[138:141], v[64:79]
	v_add_f32_e32 v96, v196, v96
	v_add_f32_e32 v96, v197, v96
	v_add_f32_e32 v96, v198, v96
	s_waitcnt lgkmcnt(0)
	v_mfma_f32_32x32x16_bf16 v[80:95], v[166:169], v[138:141], v[80:95]
	ds_read_b128 v[162:165], v209 offset:32768
	ds_read_b128 v[166:169], v209 offset:40960
	v_add_f32_e32 v96, v199, v96
	v_add_f32_e32 v96, v215, v96
	v_add_f32_e32 v96, v216, v96
	v_add_f32_e32 v96, v217, v96
	v_exp_f32_e32 v237, v97
	s_waitcnt lgkmcnt(1)
	v_mfma_f32_32x32x16_bf16 v[64:79], v[162:165], v[112:115], v[64:79]
	v_add_f32_e32 v96, v218, v96
	v_exp_f32_e32 v238, v98
	v_add_f32_e32 v96, v219, v96
	v_exp_f32_e32 v239, v99
	s_waitcnt lgkmcnt(0)
	v_mfma_f32_32x32x16_bf16 v[80:95], v[166:169], v[112:115], v[80:95]
	ds_read_b128 v[162:165], v210 offset:32768
	ds_read_b128 v[166:169], v210 offset:40960
	v_add_f32_e32 v96, v220, v96
	v_exp_f32_e32 v247, v100
	v_add_f32_e32 v96, v236, v96
	v_exp_f32_e32 v248, v101
	s_waitcnt lgkmcnt(1)
	v_mfma_f32_32x32x16_bf16 v[64:79], v[162:165], v[116:119], v[64:79]
	v_add_f32_e32 v96, v237, v96
	v_exp_f32_e32 v249, v102
	v_add_f32_e32 v96, v238, v96
	v_exp_f32_e32 v252, v103
	s_waitcnt lgkmcnt(0)
	v_mfma_f32_32x32x16_bf16 v[80:95], v[166:169], v[116:119], v[80:95]
	ds_read_b128 v[162:165], v190 offset:32768
	ds_read_b128 v[166:169], v190 offset:40960
	v_add_f32_e32 v96, v239, v96
	v_add_f32_e32 v96, v247, v96
	v_add_f32_e32 v96, v248, v96
	v_add_f32_e32 v96, v249, v96
	v_add_f32_e32 v96, v252, v96
	v_add_f32_e32 v96, v170, v96
	s_waitcnt lgkmcnt(1)
	v_mfma_f32_32x32x16_bf16 v[64:79], v[162:165], v[120:123], v[64:79]
	v_add_f32_e32 v96, v171, v96
	v_add_f32_e32 v96, v172, v96
	v_add_f32_e32 v96, v173, v96
	v_add_f32_e32 v96, v174, v96
	v_add_f32_e32 v96, v175, v96
	s_waitcnt lgkmcnt(0)
	v_mfma_f32_32x32x16_bf16 v[80:95], v[166:169], v[120:123], v[80:95]
	ds_read_b128 v[162:165], v191 offset:32768
	ds_read_b128 v[166:169], v191 offset:40960
	v_add_f32_e32 v96, v176, v96
	v_add_f32_e32 v181, v111, v96
	v_mov_b32_e32 v183, v181
	s_nop 1
	v_permlane32_swap_b32_e32 v181, v183
	v_pk_add_f32 v[96:97], v[180:181], v[182:183]
	s_waitcnt lgkmcnt(1)
	v_mfma_f32_32x32x16_bf16 v[64:79], v[162:165], v[124:127], v[64:79]
	s_nop 0
	v_add_f32_e32 v96, v128, v96
	v_add_f32_e32 v128, v96, v97
	v_cvt_pk_bf16_f32 v96, v184, v185
	v_cvt_pk_bf16_f32 v97, v186, v187
	s_waitcnt lgkmcnt(0)
	v_mfma_f32_32x32x16_bf16 v[80:95], v[166:169], v[124:127], v[80:95]
	ds_read_b128 v[162:165], v192 offset:32768
	ds_read_b128 v[166:169], v192 offset:40960
	v_cvt_pk_bf16_f32 v98, v188, v189
	v_cvt_pk_bf16_f32 v99, v196, v197
	v_cvt_pk_bf16_f32 v100, v198, v199
	v_cvt_pk_bf16_f32 v101, v215, v216
	v_cvt_pk_bf16_f32 v102, v217, v218
	v_cvt_pk_bf16_f32 v103, v219, v220
	s_waitcnt lgkmcnt(1)
	v_mfma_f32_32x32x16_bf16 v[64:79], v[162:165], v[130:133], v[64:79]
	v_cvt_pk_bf16_f32 v104, v236, v237
	v_cvt_pk_bf16_f32 v105, v238, v239
	v_cvt_pk_bf16_f32 v106, v247, v248
	v_cvt_pk_bf16_f32 v107, v249, v252
	v_cvt_pk_bf16_f32 v108, v170, v171
	s_waitcnt lgkmcnt(0)
	v_mfma_f32_32x32x16_bf16 v[80:95], v[166:169], v[130:133], v[80:95]
	ds_read_b128 v[162:165], v193 offset:32768
	ds_read_b128 v[166:169], v193 offset:40960
	ds_read_b64_tr_b16 v[180:181], v206 offset:0x4000
	ds_read_b64_tr_b16 v[182:183], v206 offset:0x4800
	ds_read_b64_tr_b16 v[184:185], v206 offset:0x5000
	ds_read_b64_tr_b16 v[186:187], v206 offset:0x5800
	ds_read_b64_tr_b16 v[216:217], v206 offset:0x6000
	ds_read_b64_tr_b16 v[218:219], v206 offset:0x6800
	ds_read_b64_tr_b16 v[220:221], v206 offset:0x7000
	ds_read_b64_tr_b16 v[222:223], v206 offset:0x7800
	v_cvt_pk_bf16_f32 v109, v172, v173
	v_cvt_pk_bf16_f32 v110, v174, v175
	v_cvt_pk_bf16_f32 v111, v176, v111
	s_nop 0
	v_permlane32_swap_b32_e32 v96, v98
	v_permlane32_swap_b32_e32 v97, v99
	s_waitcnt lgkmcnt(9)
	v_mfma_f32_32x32x16_bf16 v[64:79], v[162:165], v[134:137], v[64:79]
	v_permlane32_swap_b32_e32 v100, v102
	v_permlane32_swap_b32_e32 v101, v103
	v_permlane32_swap_b32_e32 v104, v106
	v_permlane32_swap_b32_e32 v105, v107
	v_permlane32_swap_b32_e32 v108, v110
	s_waitcnt lgkmcnt(8)
	v_mfma_f32_32x32x16_bf16 v[80:95], v[166:169], v[134:137], v[80:95]
	v_permlane32_swap_b32_e32 v109, v111
	s_waitcnt vmcnt(0)
	ds_write_b128 v211, v[146:149]
	s_nop 0
	s_waitcnt lgkmcnt(7)
	v_mfma_f32_32x32x16_bf16 v[0:15], v[96:99], v[180:183], v[0:15]
	ds_read_b64_tr_b16 v[180:181], v206 offset:0x4200
	ds_read_b64_tr_b16 v[182:183], v206 offset:0x4a00
	v_add_co_u32_e32 v166, vcc, s52, v178
	s_nop 1
	v_addc_co_u32_e32 v167, vcc, -1, v179, vcc
	v_add_co_u32_e32 v170, vcc, s53, v178
	s_nop 1
	v_addc_co_u32_e32 v171, vcc, -1, v179, vcc
	s_waitcnt lgkmcnt(7)
; #define SBAR() __builtin_amdgcn_sched_barrier(0)
; __device__ __forceinline__ void partialSM_fixed(f32x16& p0) {
;   for (int r = 0; r < 16; ++r) p0[r] = __builtin_amdgcn_exp2f(p0[r]);
; }
; __device__ __forceinline__ void finishSM(f32x16& p0, f32x16& p1, float alpha, float& l_reg, bf16x8& pa0, bf16x8& pa1, bf16x8& pa2, bf16x8& pa3) {
;   for (int r = 0; r < 16; ++r) p1[r] = __builtin_amdgcn_exp2f(p1[r]);
;   float ps = 0; for (int r = 0; r < 16; ++r) ps += p0[r]; for (int r = 0; r < 16; ++r) ps += p1[r];
;   { auto rr = __builtin_amdgcn_permlane32_swap(__float_as_uint(ps), __float_as_uint(ps), false, false);
;     ps = __uint_as_float(rr[0]) + __uint_as_float(rr[1]); }
;   l_reg = l_reg * alpha + ps;
;     ...
;   PK4(p0, 0, pa0); PK4(p0, 8, pa1); PK4(p1, 0, pa2); PK4(p1, 8, pa3);
;     ...
; }
; template <int D0, int BOFF> __device__ __forceinline__ void pv_one_i(f32x16& od, int vb, bf16x8 pa0, bf16x8 pa1, bf16x8 pa2, bf16x8 pa3) {
;   const s16x4 l0 = tr_read<BOFF + v_rd_off(D0, 0, 0)>(vb), h0 = tr_read<BOFF + v_rd_off(D0, 0, 1)>(vb), l1 = tr_read<BOFF + v_rd_off(D0, 1, 0)>(vb), h1 = tr_read<BOFF + v_rd_off(D0, 1, 1)>(vb);
;   const s16x4 l2 = tr_read<BOFF + v_rd_off(D0, 2, 0)>(vb), h2 = tr_read<BOFF + v_rd_off(D0, 2, 1)>(vb), l3 = tr_read<BOFF + v_rd_off(D0, 3, 0)>(vb), h3 = tr_read<BOFF + v_rd_off(D0, 3, 1)>(vb);
;   asm volatile("s_waitcnt lgkmcnt(0)" ::: "memory"); SBAR();
;     ...
;   od = __builtin_amdgcn_mfma_f32_32x32x16_bf16(pa0, PK(l0, h0), od, 0, 0, 0);
;   od = __builtin_amdgcn_mfma_f32_32x32x16_bf16(pa1, PK(l1, h1), od, 0, 0, 0);
;   od = __builtin_amdgcn_mfma_f32_32x32x16_bf16(pa2, PK(l2, h2), od, 0, 0, 0);
;   od = __builtin_amdgcn_mfma_f32_32x32x16_bf16(pa3, PK(l3, h3), od, 0, 0, 0);
;     ...
; }
; template <int BOFF> __device__ __forceinline__ void pv_i(f32x16* o, int vb, bf16x8 pa0, bf16x8 pa1, bf16x8 pa2, bf16x8 pa3) {
;   pv_one_i<0, BOFF>(o[0], vb, pa0, pa1, pa2, pa3); pv_one_i<1, BOFF>(o[1], vb, pa0, pa1, pa2, pa3); pv_one_i<2, BOFF>(o[2], vb, pa0, pa1, pa2, pa3); pv_one_i<3, BOFF>(o[3], vb, pa0, pa1, pa2, pa3);
; }
	v_mfma_f32_32x32x16_bf16 v[0:15], v[100:103], v[184:187], v[0:15]
	ds_read_b64_tr_b16 v[184:185], v206 offset:0x5200
	ds_read_b64_tr_b16 v[186:187], v206 offset:0x5a00
	global_load_dwordx4 v[162:165], v[166:167], off
	s_nop 0
	global_load_dwordx4 v[166:169], v[166:167], off offset:-512
	s_nop 0
	global_load_dwordx4 v[174:177], v[170:171], off
	s_nop 0
	global_load_dwordx4 v[170:173], v[170:171], off offset:-512
	s_waitcnt lgkmcnt(7)
	v_mfma_f32_32x32x16_bf16 v[0:15], v[104:107], v[216:219], v[0:15]
	ds_read_b64_tr_b16 v[216:217], v206 offset:0x6200
	ds_read_b64_tr_b16 v[218:219], v206 offset:0x6a00
	s_waitcnt lgkmcnt(7)
	v_mfma_f32_32x32x16_bf16 v[0:15], v[108:111], v[220:223], v[0:15]
	ds_read_b64_tr_b16 v[220:221], v206 offset:0x7200
	ds_read_b64_tr_b16 v[222:223], v206 offset:0x7a00
	ds_write_b128 v212, v[158:161]
	s_waitcnt lgkmcnt(7)
	v_mfma_f32_32x32x16_bf16 v[16:31], v[96:99], v[180:183], v[16:31]
	ds_read_b64_tr_b16 v[180:181], v206 offset:0x4400
	ds_read_b64_tr_b16 v[182:183], v206 offset:0x4c00
	s_waitcnt lgkmcnt(7)
	v_mfma_f32_32x32x16_bf16 v[16:31], v[100:103], v[184:187], v[16:31]
	ds_read_b64_tr_b16 v[184:185], v206 offset:0x5400
	ds_read_b64_tr_b16 v[186:187], v206 offset:0x5c00
	s_waitcnt lgkmcnt(7)
	v_mfma_f32_32x32x16_bf16 v[16:31], v[104:107], v[216:219], v[16:31]
	ds_read_b64_tr_b16 v[216:217], v206 offset:0x6400
	ds_read_b64_tr_b16 v[218:219], v206 offset:0x6c00
	s_waitcnt lgkmcnt(7)
	v_mfma_f32_32x32x16_bf16 v[16:31], v[108:111], v[220:223], v[16:31]
	ds_read_b64_tr_b16 v[220:221], v206 offset:0x7400
	ds_read_b64_tr_b16 v[222:223], v206 offset:0x7c00
	ds_write_b128 v213, v[150:153]
	s_waitcnt lgkmcnt(7)
	v_mfma_f32_32x32x16_bf16 v[32:47], v[96:99], v[180:183], v[32:47]
	ds_read_b64_tr_b16 v[180:181], v206 offset:0x4600
	ds_read_b64_tr_b16 v[182:183], v206 offset:0x4e00
	v_exp_f32_e32 v188, v72
	v_exp_f32_e32 v189, v73
	s_waitcnt lgkmcnt(7)
	v_mfma_f32_32x32x16_bf16 v[32:47], v[100:103], v[184:187], v[32:47]
	ds_read_b64_tr_b16 v[184:185], v206 offset:0x5600
	ds_read_b64_tr_b16 v[186:187], v206 offset:0x5e00
	v_exp_f32_e32 v196, v74
	v_exp_f32_e32 v197, v75
	ds_write_b128 v214, v[154:157]
	s_waitcnt lgkmcnt(8)
	v_mfma_f32_32x32x16_bf16 v[32:47], v[104:107], v[216:219], v[32:47]
	ds_read_b64_tr_b16 v[216:217], v206 offset:0x6600
	ds_read_b64_tr_b16 v[218:219], v206 offset:0x6e00
	v_exp_f32_e32 v198, v76
	v_exp_f32_e32 v199, v77
	s_waitcnt lgkmcnt(8)
	v_mfma_f32_32x32x16_bf16 v[32:47], v[108:111], v[220:223], v[32:47]
	ds_read_b64_tr_b16 v[220:221], v206 offset:0x7600
	ds_read_b64_tr_b16 v[222:223], v206 offset:0x7e00
	s_waitcnt lgkmcnt(7)
	v_mfma_f32_32x32x16_bf16 v[48:63], v[96:99], v[180:183], v[48:63]
	s_waitcnt vmcnt(4)
	v_exp_f32_e32 v180, v64
	v_exp_f32_e32 v181, v65
	v_exp_f32_e32 v182, v66
	v_exp_f32_e32 v183, v67
	s_waitcnt lgkmcnt(5)
	v_mfma_f32_32x32x16_bf16 v[48:63], v[100:103], v[184:187], v[48:63]
	v_exp_f32_e32 v184, v68
	v_exp_f32_e32 v185, v69
	v_exp_f32_e32 v186, v70
	v_exp_f32_e32 v187, v71
	s_waitcnt lgkmcnt(2)
	v_mfma_f32_32x32x16_bf16 v[48:63], v[104:107], v[216:219], v[48:63]
	v_exp_f32_e32 v216, v78
	v_exp_f32_e32 v217, v79
	s_waitcnt lgkmcnt(0)
	s_barrier
	v_mfma_f32_32x32x16_bf16 v[48:63], v[108:111], v[220:223], v[48:63]
	ds_read_b128 v[64:67], v207
	ds_read_b128 v[68:71], v207 offset:8192
	ds_read_b128 v[146:149], v208
	ds_read_b128 v[150:153], v208 offset:8192
	v_exp_f32_e32 v154, v88
	v_exp_f32_e32 v155, v89
	v_exp_f32_e32 v156, v90
	v_exp_f32_e32 v157, v91
	v_exp_f32_e32 v158, v92
	v_exp_f32_e32 v159, v93
	v_exp_f32_e32 v160, v94
	v_exp_f32_e32 v95, v95
	s_waitcnt lgkmcnt(3)
	v_mfma_f32_32x32x16_bf16 v[96:111], v[64:67], v[142:145], 0
	v_exp_f32_e32 v236, v80
	v_add_f32_e32 v80, 0, v180
	v_add_f32_e32 v80, v181, v80
	v_add_f32_e32 v80, v182, v80
	s_waitcnt lgkmcnt(2)
	v_mfma_f32_32x32x16_bf16 v[64:79], v[68:71], v[142:145], 0
	v_add_f32_e32 v80, v183, v80
	v_add_f32_e32 v80, v184, v80
	v_add_f32_e32 v80, v185, v80
	s_waitcnt lgkmcnt(1)
	v_mfma_f32_32x32x16_bf16 v[96:111], v[146:149], v[138:141], v[96:111]
	v_add_f32_e32 v80, v186, v80
	v_add_f32_e32 v80, v187, v80
	v_add_f32_e32 v80, v188, v80
	s_waitcnt lgkmcnt(0)
	v_mfma_f32_32x32x16_bf16 v[64:79], v[150:153], v[138:141], v[64:79]
	ds_read_b128 v[146:149], v209
	ds_read_b128 v[150:153], v209 offset:8192
	v_add_f32_e32 v80, v189, v80
	v_add_f32_e32 v80, v196, v80
	v_add_f32_e32 v80, v197, v80
	v_add_f32_e32 v80, v198, v80
	v_exp_f32_e32 v237, v81
	s_waitcnt lgkmcnt(1)
	v_mfma_f32_32x32x16_bf16 v[96:111], v[146:149], v[112:115], v[96:111]
	v_add_f32_e32 v80, v199, v80
	v_exp_f32_e32 v238, v82
	v_add_f32_e32 v80, v216, v80
	v_exp_f32_e32 v239, v83
	s_waitcnt lgkmcnt(0)
	v_mfma_f32_32x32x16_bf16 v[64:79], v[150:153], v[112:115], v[64:79]
	ds_read_b128 v[146:149], v210
	ds_read_b128 v[150:153], v210 offset:8192
	v_add_f32_e32 v80, v217, v80
	v_exp_f32_e32 v247, v84
	v_add_f32_e32 v80, v236, v80
	v_exp_f32_e32 v248, v85
	s_waitcnt lgkmcnt(1)
	v_mfma_f32_32x32x16_bf16 v[96:111], v[146:149], v[116:119], v[96:111]
	v_add_f32_e32 v80, v237, v80
	v_exp_f32_e32 v249, v86
	v_add_f32_e32 v80, v238, v80
	v_exp_f32_e32 v252, v87
	s_waitcnt lgkmcnt(0)
	v_mfma_f32_32x32x16_bf16 v[64:79], v[150:153], v[116:119], v[64:79]
	ds_read_b128 v[146:149], v190 offset:0
	ds_read_b128 v[150:153], v190 offset:8192
	v_add_f32_e32 v80, v239, v80
	v_add_f32_e32 v80, v247, v80
	v_add_f32_e32 v80, v248, v80
	v_add_f32_e32 v80, v249, v80
	v_add_f32_e32 v80, v252, v80
	v_add_f32_e32 v80, v154, v80
	s_waitcnt lgkmcnt(1)
	v_mfma_f32_32x32x16_bf16 v[96:111], v[146:149], v[120:123], v[96:111]
	v_add_f32_e32 v80, v155, v80
	v_add_f32_e32 v80, v156, v80
	v_add_f32_e32 v80, v157, v80
	v_add_f32_e32 v80, v158, v80
	v_add_f32_e32 v80, v159, v80
	s_waitcnt lgkmcnt(0)
; #define SBAR() __builtin_amdgcn_sched_barrier(0)
; #define SLOAD(i, k0) do { sr_[i].vs0 = ld8(&Vh[(long)((k0) + sr) * LDK + sc]); sr_[i].vs1 = ld8(&Vh[(long)((k0) + 32 + sr) * LDK + sc]); \
;     sr_[i].ks0 = ld8(&Kh[(long)((k0) + sr) * LDK + sc]); sr_[i].ks1 = ld8(&Kh[(long)((k0) + 32 + sr) * LDK + sc]); } while (0)
; #define SWAIT() asm volatile("s_waitcnt vmcnt(4)" ::: "memory")
; #define NOP_() do { } while (0)
; template <int D0, int BOFF> __device__ __forceinline__ void pv_one_i(f32x16& od, int vb, bf16x8 pa0, bf16x8 pa1, bf16x8 pa2, bf16x8 pa3) {
;   const s16x4 l0 = tr_read<BOFF + v_rd_off(D0, 0, 0)>(vb), h0 = tr_read<BOFF + v_rd_off(D0, 0, 1)>(vb), l1 = tr_read<BOFF + v_rd_off(D0, 1, 0)>(vb), h1 = tr_read<BOFF + v_rd_off(D0, 1, 1)>(vb);
;   const s16x4 l2 = tr_read<BOFF + v_rd_off(D0, 2, 0)>(vb), h2 = tr_read<BOFF + v_rd_off(D0, 2, 1)>(vb), l3 = tr_read<BOFF + v_rd_off(D0, 3, 0)>(vb), h3 = tr_read<BOFF + v_rd_off(D0, 3, 1)>(vb);
;   asm volatile("s_waitcnt lgkmcnt(0)" ::: "memory"); SBAR();
;     ...
;   od = __builtin_amdgcn_mfma_f32_32x32x16_bf16(pa0, PK(l0, h0), od, 0, 0, 0);
;   od = __builtin_amdgcn_mfma_f32_32x32x16_bf16(pa1, PK(l1, h1), od, 0, 0, 0);
;   od = __builtin_amdgcn_mfma_f32_32x32x16_bf16(pa2, PK(l2, h2), od, 0, 0, 0);
;   od = __builtin_amdgcn_mfma_f32_32x32x16_bf16(pa3, PK(l3, h3), od, 0, 0, 0);
;     ...
; }
; template <int BOFF> __device__ __forceinline__ void pv_i(f32x16* o, int vb, bf16x8 pa0, bf16x8 pa1, bf16x8 pa2, bf16x8 pa3) {
;   pv_one_i<0, BOFF>(o[0], vb, pa0, pa1, pa2, pa3); pv_one_i<1, BOFF>(o[1], vb, pa0, pa1, pa2, pa3); pv_one_i<2, BOFF>(o[2], vb, pa0, pa1, pa2, pa3); pv_one_i<3, BOFF>(o[3], vb, pa0, pa1, pa2, pa3);
; }
; template <bool PARTIAL, bool FIXED> ...
;     ...
;   for (; j + 6 < NT; j += 6) {
;     HALF_B(1, 0, SLOAD(1, (j + 2) * KVBLK), do { SWAIT(); SWRITE_I(2, 0); } while (0));
;     HALF_A(2, 1, NOP_(), SLOAD(0, (j + 3) * KVBLK), do { SWAIT(); SWRITE_I(0, 1); } while (0));
;     HALF_B(0, 2, SLOAD(1, (j + 4) * KVBLK), do { SWAIT(); SWRITE_I(1, 0); } while (0));
;     HALF_A(1, 0, NOP_(), SLOAD(0, (j + 5) * KVBLK), do { SWAIT(); SWRITE_I(2, 1); } while (0));
;     HALF_B(2, 1, SLOAD(1, (j + 6) * KVBLK), do { SWAIT(); SWRITE_I(0, 0); } while (0));
;     HALF_A(0, 2, NOP_(), SLOAD(0, (j + 7) * KVBLK), do { SWAIT(); SWRITE_I(1, 1); } while (0));
	v_mfma_f32_32x32x16_bf16 v[64:79], v[150:153], v[120:123], v[64:79]
	ds_read_b128 v[146:149], v191 offset:0
	ds_read_b128 v[150:153], v191 offset:8192
	v_add_f32_e32 v80, v160, v80
	v_add_f32_e32 v80, v95, v80
	v_mov_b32_e32 v81, v80
	s_nop 1
	v_permlane32_swap_b32_e32 v80, v81
	v_add_f32_e32 v80, v80, v81
	s_waitcnt lgkmcnt(1)
	v_mfma_f32_32x32x16_bf16 v[96:111], v[146:149], v[124:127], v[96:111]
	v_add_f32_e32 v215, v128, v80
	v_cvt_pk_bf16_f32 v80, v180, v181
	v_cvt_pk_bf16_f32 v81, v182, v183
	v_cvt_pk_bf16_f32 v82, v184, v185
	v_cvt_pk_bf16_f32 v83, v186, v187
	s_waitcnt lgkmcnt(0)
	v_mfma_f32_32x32x16_bf16 v[64:79], v[150:153], v[124:127], v[64:79]
	ds_read_b128 v[146:149], v192 offset:0
	ds_read_b128 v[150:153], v192 offset:8192
	v_cvt_pk_bf16_f32 v84, v188, v189
	v_cvt_pk_bf16_f32 v85, v196, v197
	v_cvt_pk_bf16_f32 v86, v198, v199
	v_cvt_pk_bf16_f32 v87, v216, v217
	v_cvt_pk_bf16_f32 v88, v236, v237
	v_cvt_pk_bf16_f32 v89, v238, v239
	s_waitcnt lgkmcnt(1)
	v_mfma_f32_32x32x16_bf16 v[96:111], v[146:149], v[130:133], v[96:111]
	v_cvt_pk_bf16_f32 v90, v247, v248
	v_cvt_pk_bf16_f32 v91, v249, v252
	v_cvt_pk_bf16_f32 v92, v154, v155
	v_cvt_pk_bf16_f32 v93, v156, v157
	v_cvt_pk_bf16_f32 v94, v158, v159
	s_waitcnt lgkmcnt(0)
	v_mfma_f32_32x32x16_bf16 v[64:79], v[150:153], v[130:133], v[64:79]
	ds_read_b128 v[146:149], v193 offset:0
	ds_read_b128 v[150:153], v193 offset:8192
	ds_read_b64_tr_b16 v[180:181], v206 offset:0x8000
	ds_read_b64_tr_b16 v[182:183], v206 offset:0x8800
	ds_read_b64_tr_b16 v[184:185], v206 offset:0x9000
	ds_read_b64_tr_b16 v[186:187], v206 offset:0x9800
	ds_read_b64_tr_b16 v[216:217], v206 offset:0xa000
	ds_read_b64_tr_b16 v[218:219], v206 offset:0xa800
	ds_read_b64_tr_b16 v[220:221], v206 offset:0xb000
	ds_read_b64_tr_b16 v[222:223], v206 offset:0xb800
	v_cvt_pk_bf16_f32 v95, v160, v95
	s_nop 0
	v_permlane32_swap_b32_e32 v80, v82
	v_permlane32_swap_b32_e32 v81, v83
	v_permlane32_swap_b32_e32 v84, v86
	v_permlane32_swap_b32_e32 v85, v87
	s_waitcnt lgkmcnt(9)
	v_mfma_f32_32x32x16_bf16 v[96:111], v[146:149], v[134:137], v[96:111]
	v_permlane32_swap_b32_e32 v88, v90
	v_permlane32_swap_b32_e32 v89, v91
	v_permlane32_swap_b32_e32 v92, v94
	v_permlane32_swap_b32_e32 v93, v95
	s_waitcnt lgkmcnt(8)
	v_mfma_f32_32x32x16_bf16 v[64:79], v[150:153], v[134:137], v[64:79]
	s_waitcnt vmcnt(0)
	ds_write_b128 v211, v[162:165] offset:16384
	s_nop 0
	s_waitcnt lgkmcnt(7)
	v_mfma_f32_32x32x16_bf16 v[0:15], v[80:83], v[180:183], v[0:15]
	ds_read_b64_tr_b16 v[180:181], v206 offset:0x8200
	ds_read_b64_tr_b16 v[182:183], v206 offset:0x8a00
	v_add_co_u32_e32 v150, vcc, s58, v178
	s_nop 1
	v_addc_co_u32_e32 v151, vcc, -1, v179, vcc
	s_waitcnt lgkmcnt(7)
	v_mfma_f32_32x32x16_bf16 v[0:15], v[84:87], v[184:187], v[0:15]
	ds_read_b64_tr_b16 v[184:185], v206 offset:0x9200
	ds_read_b64_tr_b16 v[186:187], v206 offset:0x9a00
	global_load_dwordx4 v[146:149], v[150:151], off
	global_load_dwordx4 v[154:157], v[150:151], off offset:-512
	s_nop 0
	global_load_dwordx4 v[150:153], v[178:179], off
	global_load_dwordx4 v[158:161], v[178:179], off offset:-512
	s_waitcnt lgkmcnt(7)
	v_mfma_f32_32x32x16_bf16 v[0:15], v[88:91], v[216:219], v[0:15]
	ds_read_b64_tr_b16 v[216:217], v206 offset:0xa200
	ds_read_b64_tr_b16 v[218:219], v206 offset:0xaa00
	s_waitcnt lgkmcnt(7)
	v_mfma_f32_32x32x16_bf16 v[0:15], v[92:95], v[220:223], v[0:15]
	ds_read_b64_tr_b16 v[220:221], v206 offset:0xb200
	ds_read_b64_tr_b16 v[222:223], v206 offset:0xba00
	ds_write_b128 v212, v[174:177] offset:16384
	s_waitcnt lgkmcnt(7)
	v_mfma_f32_32x32x16_bf16 v[16:31], v[80:83], v[180:183], v[16:31]
	ds_read_b64_tr_b16 v[180:181], v206 offset:0x8400
	ds_read_b64_tr_b16 v[182:183], v206 offset:0x8c00
	s_waitcnt lgkmcnt(7)
	v_mfma_f32_32x32x16_bf16 v[16:31], v[84:87], v[184:187], v[16:31]
	ds_read_b64_tr_b16 v[184:185], v206 offset:0x9400
	ds_read_b64_tr_b16 v[186:187], v206 offset:0x9c00
	s_waitcnt lgkmcnt(7)
	v_mfma_f32_32x32x16_bf16 v[16:31], v[88:91], v[216:219], v[16:31]
	ds_read_b64_tr_b16 v[216:217], v206 offset:0xa400
	ds_read_b64_tr_b16 v[218:219], v206 offset:0xac00
	s_waitcnt lgkmcnt(7)
	v_mfma_f32_32x32x16_bf16 v[16:31], v[92:95], v[220:223], v[16:31]
	ds_read_b64_tr_b16 v[220:221], v206 offset:0xb400
	ds_read_b64_tr_b16 v[222:223], v206 offset:0xbc00
	ds_write_b128 v213, v[166:169] offset:16384
	s_waitcnt lgkmcnt(7)
	v_mfma_f32_32x32x16_bf16 v[32:47], v[80:83], v[180:183], v[32:47]
	ds_read_b64_tr_b16 v[180:181], v206 offset:0x8600
	ds_read_b64_tr_b16 v[182:183], v206 offset:0x8e00
	v_exp_f32_e32 v229, v96
	v_exp_f32_e32 v243, v97
	s_waitcnt lgkmcnt(7)
	v_mfma_f32_32x32x16_bf16 v[32:47], v[84:87], v[184:187], v[32:47]
	ds_read_b64_tr_b16 v[184:185], v206 offset:0x9600
	ds_read_b64_tr_b16 v[186:187], v206 offset:0x9e00
	v_exp_f32_e32 v244, v98
	v_exp_f32_e32 v246, v99
	ds_write_b128 v214, v[170:173] offset:16384
	s_waitcnt lgkmcnt(8)
	v_mfma_f32_32x32x16_bf16 v[32:47], v[88:91], v[216:219], v[32:47]
	ds_read_b64_tr_b16 v[216:217], v206 offset:0xa600
	ds_read_b64_tr_b16 v[218:219], v206 offset:0xae00
	v_exp_f32_e32 v242, v100
	v_exp_f32_e32 v245, v101
	s_waitcnt lgkmcnt(8)
	v_mfma_f32_32x32x16_bf16 v[32:47], v[92:95], v[220:223], v[32:47]
	ds_read_b64_tr_b16 v[220:221], v206 offset:0xb600
	ds_read_b64_tr_b16 v[222:223], v206 offset:0xbe00
	v_exp_f32_e32 v227, v102
	v_exp_f32_e32 v228, v103
	s_waitcnt lgkmcnt(7)
	v_mfma_f32_32x32x16_bf16 v[48:63], v[80:83], v[180:183], v[48:63]
	s_waitcnt lgkmcnt(5)
	v_mfma_f32_32x32x16_bf16 v[48:63], v[84:87], v[184:187], v[48:63]
	v_exp_f32_e32 v226, v105
	v_exp_f32_e32 v224, v106
	v_exp_f32_e32 v225, v107
	s_waitcnt vmcnt(4)
	s_add_i32 s28, s28, 6
	v_lshl_add_u64 v[178:179], v[178:179], 0, s[60:61]
	s_waitcnt lgkmcnt(2)
	v_mfma_f32_32x32x16_bf16 v[48:63], v[88:91], v[216:219], v[48:63]
	v_exp_f32_e32 v219, v110
	s_cmpk_lt_u32 s28, 0x75
	s_waitcnt lgkmcnt(0)
	v_mfma_f32_32x32x16_bf16 v[48:63], v[92:95], v[220:223], v[48:63]
	v_exp_f32_e32 v223, v104
	v_exp_f32_e32 v220, v108
	v_exp_f32_e32 v222, v109
	v_exp_f32_e32 v221, v111
	s_cbranch_scc1 .LBB0_352
; #define SBAR() __builtin_amdgcn_sched_barrier(0)
; #define SWRITE_I(B, i) do { LDSV(wv0 + (B) * 16384) = sr_[i].vs0; LDSV(wv1 + (B) * 16384) = sr_[i].vs1; LDSV(wk0 + (B) * 16384) = sr_[i].ks0; LDSV(wk1 + (B) * 16384) = sr_[i].ks1; } while (0)
; #define NOP_() do { } while (0)
; __device__ __forceinline__ void finishSM(f32x16& p0, f32x16& p1, float alpha, float& l_reg, bf16x8& pa0, bf16x8& pa1, bf16x8& pa2, bf16x8& pa3) {
;   for (int r = 0; r < 16; ++r) p1[r] = __builtin_amdgcn_exp2f(p1[r]);
;   float ps = 0; for (int r = 0; r < 16; ++r) ps += p0[r]; for (int r = 0; r < 16; ++r) ps += p1[r];
;   { auto rr = __builtin_amdgcn_permlane32_swap(__float_as_uint(ps), __float_as_uint(ps), false, false);
;     ps = __uint_as_float(rr[0]) + __uint_as_float(rr[1]); }
;   l_reg = l_reg * alpha + ps;
;     ...
;   PK4(p0, 0, pa0); PK4(p0, 8, pa1); PK4(p1, 0, pa2); PK4(p1, 8, pa3);
;     ...
; }
; template <bool PARTIAL, bool FIXED> ...
;     ...
;   if constexpr (!PARTIAL) { const int i1 = tid & 255;
;     warm0 = *(const unsigned*)(Qb_n + (long)(tid >> 1) * LDQ + (tid & 1) * 64);
;     warm1 = *(const unsigned*)((tid < 256 ? Kh_n : Vh_n) + (long)(i1 >> 1) * LDK + (i1 & 1) * 64); }
;   HALF_B(1, 0, NOP_(), SWRITE_I(2, 0));
;   HALF_A(2, 1, do { if (mask_last) { asm volatile("; masked tail tile" ::: "memory"); const float NEG = -INFINITY; \
;       _Pragma("unroll") for (int r = 8; r < 16; ++r) pA0[r] = NEG; _Pragma("unroll") for (int r = 0; r < 16; ++r) pA1[r] = NEG; } } while (0), NOP_(), NOP_());
;     ...
;   SBAR(); finishSM(pA0, pA1, alA, l_reg, pa0, pa1, pa2, pa3); SBAR();
	v_mov_b32_e32 v252, 0x7fc00000
	v_readlane_b32 s8, v255, 42
	v_readlane_b32 s9, v255, 43
	s_add_u32 s2, s8, s6
	s_addc_u32 s3, s9, s7
	s_lshl_b32 s4, s65, 1
	s_add_u32 s2, s2, s4
	s_addc_u32 s3, s3, 0
	v_ashrrev_i32_e32 v82, 1, v195
	v_mov_b64_e32 v[80:81], s[2:3]
	v_mad_i64_i32 v[80:81], s[2:3], v82, s17, v[80:81]
	v_lshlrev_b32_e32 v82, 7, v195
	v_and_b32_e32 v128, 0x80, v82
	v_lshl_add_u64 v[80:81], v[80:81], 0, v[128:129]
	s_add_u32 s4, s8, s64
	global_load_dword v216, v[80:81], off
	v_cmp_gt_i32_e32 vcc, s14, v195
	v_mov_b32_e32 v80, 0xa00
	v_mov_b32_e32 v81, 0x800
	s_addc_u32 s5, s9, s57
	v_cndmask_b32_e32 v80, v80, v81, vcc
	v_mov_b32_e32 v81, v129
	v_bfe_u32 v82, v195, 1, 7
	v_lshl_add_u64 v[80:81], s[4:5], 0, v[80:81]
	s_lshl_b32 s46, s56, 1
	v_mul_u32_u24_e32 v82, 0x600, v82
	v_lshl_add_u64 v[80:81], v[80:81], 0, s[46:47]
	v_lshlrev_b32_e32 v82, 1, v82
	v_mov_b32_e32 v83, v129
	v_lshl_add_u64 v[80:81], v[80:81], 0, v[82:83]
	v_lshl_add_u64 v[80:81], v[80:81], 0, v[128:129]
	global_load_dword v217, v[80:81], off
	v_and_b32_e32 v247, 0x3fffffc0, v195
	s_waitcnt lgkmcnt(0)
	s_barrier
	ds_read_b128 v[80:83], v207 offset:16384
	ds_read_b128 v[96:99], v207 offset:24576
	ds_read_b128 v[100:103], v208 offset:16384
	ds_read_b128 v[170:173], v208 offset:24576
	v_exp_f32_e32 v104, v68
	v_exp_f32_e32 v105, v69
	s_waitcnt lgkmcnt(3)
	v_mfma_f32_32x32x16_bf16 v[80:95], v[80:83], v[142:145], 0
	v_exp_f32_e32 v106, v70
	v_exp_f32_e32 v107, v71
	v_exp_f32_e32 v108, v72
	v_exp_f32_e32 v109, v73
	v_exp_f32_e32 v110, v74
	v_exp_f32_e32 v111, v75
	v_exp_f32_e32 v196, v76
	s_waitcnt lgkmcnt(1)
	v_mfma_f32_32x32x16_bf16 v[80:95], v[100:103], v[138:141], v[80:95]
	ds_read_b128 v[100:103], v209 offset:16384
	ds_read_b128 v[162:165], v209 offset:24576
	v_exp_f32_e32 v197, v77
	v_exp_f32_e32 v198, v78
	v_exp_f32_e32 v79, v79
	s_waitcnt lgkmcnt(1)
	v_mfma_f32_32x32x16_bf16 v[80:95], v[100:103], v[112:115], v[80:95]
	ds_read_b128 v[100:103], v210 offset:16384
	ds_read_b128 v[166:169], v210 offset:24576
	s_waitcnt lgkmcnt(1)
	v_mfma_f32_32x32x16_bf16 v[80:95], v[100:103], v[116:119], v[80:95]
	ds_read_b128 v[100:103], v190 offset:16384
	ds_read_b128 v[174:177], v190 offset:24576
	s_waitcnt lgkmcnt(1)
	v_mfma_f32_32x32x16_bf16 v[80:95], v[100:103], v[120:123], v[80:95]
	ds_read_b128 v[100:103], v191 offset:16384
	ds_read_b128 v[178:181], v191 offset:24576
	s_waitcnt lgkmcnt(1)
	v_mfma_f32_32x32x16_bf16 v[80:95], v[100:103], v[124:127], v[80:95]
	ds_read_b128 v[100:103], v192 offset:16384
	ds_read_b128 v[182:185], v192 offset:24576
	s_waitcnt lgkmcnt(1)
	v_mfma_f32_32x32x16_bf16 v[80:95], v[100:103], v[130:133], v[80:95]
	ds_read_b128 v[100:103], v193 offset:16384
	ds_read_b128 v[186:189], v193 offset:24576
	s_waitcnt lgkmcnt(1)
	v_mfma_f32_32x32x16_bf16 v[80:95], v[100:103], v[134:137], v[80:95]
	v_exp_f32_e32 v100, v64
	v_add_f32_e32 v64, 0, v229
	v_add_f32_e32 v64, v243, v64
	v_add_f32_e32 v64, v244, v64
	v_add_f32_e32 v64, v246, v64
	v_add_f32_e32 v64, v242, v64
	v_add_f32_e32 v64, v245, v64
	v_add_f32_e32 v64, v227, v64
	v_add_f32_e32 v64, v228, v64
	v_add_f32_e32 v64, v223, v64
	v_add_f32_e32 v64, v226, v64
	v_add_f32_e32 v64, v224, v64
	v_add_f32_e32 v64, v225, v64
	v_add_f32_e32 v64, v220, v64
	v_exp_f32_e32 v101, v65
	v_add_f32_e32 v64, v222, v64
	v_exp_f32_e32 v102, v66
	v_add_f32_e32 v64, v219, v64
	v_exp_f32_e32 v103, v67
	v_add_f32_e32 v64, v221, v64
	v_add_f32_e32 v64, v100, v64
	v_add_f32_e32 v64, v101, v64
	v_add_f32_e32 v64, v102, v64
	v_add_f32_e32 v64, v103, v64
	v_add_f32_e32 v64, v104, v64
	v_add_f32_e32 v64, v105, v64
	v_add_f32_e32 v64, v106, v64
	v_add_f32_e32 v64, v107, v64
	v_add_f32_e32 v64, v108, v64
	v_add_f32_e32 v64, v109, v64
	v_add_f32_e32 v64, v110, v64
	v_add_f32_e32 v64, v111, v64
	v_add_f32_e32 v64, v196, v64
	v_add_f32_e32 v64, v197, v64
	v_add_f32_e32 v64, v198, v64
	v_add_f32_e32 v128, v79, v64
	v_mov_b32_e32 v218, v128
	s_nop 1
	v_permlane32_swap_b32_e32 v128, v218
	v_cvt_pk_bf16_f32 v64, v229, v243
	v_cvt_pk_bf16_f32 v65, v244, v246
	v_cvt_pk_bf16_f32 v66, v242, v245
	v_cvt_pk_bf16_f32 v67, v227, v228
	v_cvt_pk_bf16_f32 v68, v223, v226
	v_cvt_pk_bf16_f32 v69, v224, v225
	v_cvt_pk_bf16_f32 v70, v220, v222
	v_cvt_pk_bf16_f32 v71, v219, v221
	v_cvt_pk_bf16_f32 v72, v100, v101
	v_cvt_pk_bf16_f32 v73, v102, v103
	v_cvt_pk_bf16_f32 v74, v104, v105
	v_cvt_pk_bf16_f32 v75, v106, v107
	v_cvt_pk_bf16_f32 v76, v108, v109
	v_cvt_pk_bf16_f32 v77, v110, v111
	v_cvt_pk_bf16_f32 v78, v196, v197
	v_cvt_pk_bf16_f32 v79, v198, v79
	s_nop 0
	v_permlane32_swap_b32_e32 v64, v66
	v_permlane32_swap_b32_e32 v65, v67
	v_permlane32_swap_b32_e32 v68, v70
	v_permlane32_swap_b32_e32 v69, v71
	v_permlane32_swap_b32_e32 v72, v74
	v_permlane32_swap_b32_e32 v73, v75
	v_permlane32_swap_b32_e32 v76, v78
	v_permlane32_swap_b32_e32 v77, v79
	ds_read_b64_tr_b16 v[100:101], v206 offset:0
	ds_read_b64_tr_b16 v[102:103], v206 offset:0x800
	ds_read_b64_tr_b16 v[104:105], v206 offset:0x1000
	ds_read_b64_tr_b16 v[106:107], v206 offset:0x1800
	ds_read_b64_tr_b16 v[108:109], v206 offset:0x2000
	ds_read_b64_tr_b16 v[110:111], v206 offset:0x2800
	ds_read_b64_tr_b16 v[220:221], v206 offset:0x3000
	ds_read_b64_tr_b16 v[222:223], v206 offset:0x3800
	s_waitcnt lgkmcnt(0)
	s_nop 0
	v_mfma_f32_32x32x16_bf16 v[0:15], v[64:67], v[100:103], v[0:15]
	ds_read_b64_tr_b16 v[100:101], v206 offset:0x200
	ds_read_b64_tr_b16 v[102:103], v206 offset:0xa00
	v_mfma_f32_32x32x16_bf16 v[0:15], v[68:71], v[104:107], v[0:15]
	ds_read_b64_tr_b16 v[104:105], v206 offset:0x1200
	ds_read_b64_tr_b16 v[106:107], v206 offset:0x1a00
	v_mfma_f32_32x32x16_bf16 v[0:15], v[72:75], v[108:111], v[0:15]
	ds_read_b64_tr_b16 v[108:109], v206 offset:0x2200
	ds_read_b64_tr_b16 v[110:111], v206 offset:0x2a00
	v_mfma_f32_32x32x16_bf16 v[0:15], v[76:79], v[220:223], v[0:15]
	ds_read_b64_tr_b16 v[220:221], v206 offset:0x3200
	ds_read_b64_tr_b16 v[222:223], v206 offset:0x3a00
	s_waitcnt lgkmcnt(0)
; #define SBAR() __builtin_amdgcn_sched_barrier(0)
; template <int BOFF> __device__ __forceinline__ void qkt_i(f32x16& p0, f32x16& p1, const int (&kb)[4], const bf16x8* qr) {
;   p0 = f32x16{}; p1 = f32x16{};
; #pragma unroll
;   for (int d0 = 0; d0 < 8; ++d0) { const int off = BOFF + (d0 >> 2) * 128;
;     const bf16x8 b0 = LDSV(kb[d0 & 3] + off), b1 = LDSV(kb[d0 & 3] + off + 8192);
;     p0 = __builtin_amdgcn_mfma_f32_32x32x16_bf16(b0, qr[d0], p0, 0, 0, 0);
;     p1 = __builtin_amdgcn_mfma_f32_32x32x16_bf16(b1, qr[d0], p1, 0, 0, 0); }
; }
; template <int D0, int BOFF> __device__ __forceinline__ void pv_one_i(f32x16& od, int vb, bf16x8 pa0, bf16x8 pa1, bf16x8 pa2, bf16x8 pa3) {
;   const s16x4 l0 = tr_read<BOFF + v_rd_off(D0, 0, 0)>(vb), h0 = tr_read<BOFF + v_rd_off(D0, 0, 1)>(vb), l1 = tr_read<BOFF + v_rd_off(D0, 1, 0)>(vb), h1 = tr_read<BOFF + v_rd_off(D0, 1, 1)>(vb);
;   const s16x4 l2 = tr_read<BOFF + v_rd_off(D0, 2, 0)>(vb), h2 = tr_read<BOFF + v_rd_off(D0, 2, 1)>(vb), l3 = tr_read<BOFF + v_rd_off(D0, 3, 0)>(vb), h3 = tr_read<BOFF + v_rd_off(D0, 3, 1)>(vb);
;   asm volatile("s_waitcnt lgkmcnt(0)" ::: "memory"); SBAR();
;     ...
;   od = __builtin_amdgcn_mfma_f32_32x32x16_bf16(pa0, PK(l0, h0), od, 0, 0, 0);
;   od = __builtin_amdgcn_mfma_f32_32x32x16_bf16(pa1, PK(l1, h1), od, 0, 0, 0);
;   od = __builtin_amdgcn_mfma_f32_32x32x16_bf16(pa2, PK(l2, h2), od, 0, 0, 0);
;   od = __builtin_amdgcn_mfma_f32_32x32x16_bf16(pa3, PK(l3, h3), od, 0, 0, 0);
;     ...
; }
; template <int BOFF> __device__ __forceinline__ void pv_i(f32x16* o, int vb, bf16x8 pa0, bf16x8 pa1, bf16x8 pa2, bf16x8 pa3) {
;   pv_one_i<0, BOFF>(o[0], vb, pa0, pa1, pa2, pa3); pv_one_i<1, BOFF>(o[1], vb, pa0, pa1, pa2, pa3); pv_one_i<2, BOFF>(o[2], vb, pa0, pa1, pa2, pa3); pv_one_i<3, BOFF>(o[3], vb, pa0, pa1, pa2, pa3);
; }
	v_mfma_f32_32x32x16_bf16 v[16:31], v[64:67], v[100:103], v[16:31]
	ds_read_b64_tr_b16 v[100:101], v206 offset:0x400
	ds_read_b64_tr_b16 v[102:103], v206 offset:0xc00
	v_mfma_f32_32x32x16_bf16 v[16:31], v[68:71], v[104:107], v[16:31]
	ds_read_b64_tr_b16 v[104:105], v206 offset:0x1400
	ds_read_b64_tr_b16 v[106:107], v206 offset:0x1c00
	v_mfma_f32_32x32x16_bf16 v[16:31], v[72:75], v[108:111], v[16:31]
	ds_read_b64_tr_b16 v[108:109], v206 offset:0x2400
	ds_read_b64_tr_b16 v[110:111], v206 offset:0x2c00
	v_mfma_f32_32x32x16_bf16 v[16:31], v[76:79], v[220:223], v[16:31]
	ds_read_b64_tr_b16 v[220:221], v206 offset:0x3400
	ds_read_b64_tr_b16 v[222:223], v206 offset:0x3c00
	s_waitcnt lgkmcnt(0)
	v_mfma_f32_32x32x16_bf16 v[32:47], v[64:67], v[100:103], v[32:47]
	ds_read_b64_tr_b16 v[100:101], v206 offset:0x600
	ds_read_b64_tr_b16 v[102:103], v206 offset:0xe00
	v_mfma_f32_32x32x16_bf16 v[32:47], v[68:71], v[104:107], v[32:47]
	ds_read_b64_tr_b16 v[104:105], v206 offset:0x1600
	ds_read_b64_tr_b16 v[106:107], v206 offset:0x1e00
	v_mfma_f32_32x32x16_bf16 v[32:47], v[72:75], v[108:111], v[32:47]
	ds_read_b64_tr_b16 v[108:109], v206 offset:0x2600
	ds_read_b64_tr_b16 v[110:111], v206 offset:0x2e00
	v_mfma_f32_32x32x16_bf16 v[32:47], v[76:79], v[220:223], v[32:47]
	ds_read_b64_tr_b16 v[220:221], v206 offset:0x3600
	ds_read_b64_tr_b16 v[222:223], v206 offset:0x3e00
	s_waitcnt lgkmcnt(0)
	v_mfma_f32_32x32x16_bf16 v[48:63], v[64:67], v[100:103], v[48:63]
	s_waitcnt vmcnt(5)
	ds_write_b128 v211, v[146:149] offset:32768
	s_waitcnt vmcnt(3)
	ds_write_b128 v212, v[150:153] offset:32768
	ds_write_b128 v213, v[154:157] offset:32768
	s_waitcnt vmcnt(2)
	ds_write_b128 v214, v[158:161] offset:32768
	s_waitcnt lgkmcnt(0)
	s_barrier
	v_mfma_f32_32x32x16_bf16 v[48:63], v[68:71], v[104:107], v[48:63]
	v_mfma_f32_32x32x16_bf16 v[48:63], v[72:75], v[108:111], v[48:63]
	v_mfma_f32_32x32x16_bf16 v[48:63], v[76:79], v[220:223], v[48:63]
	ds_read_b128 v[64:67], v207 offset:32768
	ds_read_b128 v[100:103], v208 offset:32768
	s_add_i32 s2, 0, 0x18000
	s_waitcnt lgkmcnt(1)
	v_mfma_f32_32x32x16_bf16 v[64:79], v[64:67], v[142:145], 0
	s_waitcnt lgkmcnt(0)
	v_mfma_f32_32x32x16_bf16 v[64:79], v[100:103], v[138:141], v[64:79]
	ds_read_b128 v[100:103], v209 offset:32768
	s_waitcnt lgkmcnt(0)
	v_mfma_f32_32x32x16_bf16 v[64:79], v[100:103], v[112:115], v[64:79]
	ds_read_b128 v[100:103], v210 offset:32768
	s_waitcnt lgkmcnt(0)
	v_mfma_f32_32x32x16_bf16 v[64:79], v[100:103], v[116:119], v[64:79]
	ds_read_b128 v[100:103], v190 offset:32768
	s_waitcnt lgkmcnt(0)
	v_mfma_f32_32x32x16_bf16 v[64:79], v[100:103], v[120:123], v[64:79]
	ds_read_b128 v[100:103], v191 offset:32768
	s_waitcnt lgkmcnt(0)
	v_mfma_f32_32x32x16_bf16 v[64:79], v[100:103], v[124:127], v[64:79]
	ds_read_b128 v[100:103], v192 offset:32768
	s_waitcnt lgkmcnt(0)
	v_mfma_f32_32x32x16_bf16 v[64:79], v[100:103], v[130:133], v[64:79]
	ds_read_b128 v[100:103], v193 offset:32768
	s_waitcnt lgkmcnt(0)
	v_and_b32_e32 v190, 63, v195
	v_lshlrev_b32_e32 v191, 4, v195
	v_and_b32_e32 v192, 31, v195
	v_bfe_u32 v193, v195, 5, 1
	v_mfma_f32_32x32x16_bf16 v[64:79], v[100:103], v[134:137], v[64:79]
	v_mfma_f32_32x32x16_bf16 v[96:111], v[96:99], v[142:145], 0
	s_nop 10
	v_exp_f32_e32 v72, v80
	v_exp_f32_e32 v80, v81
	v_exp_f32_e32 v73, v82
	v_exp_f32_e32 v81, v83
	v_exp_f32_e32 v74, v84
	v_add_f32_e32 v84, 0, v72
	v_exp_f32_e32 v82, v85
	v_mfma_f32_32x32x16_bf16 v[96:111], v[170:173], v[138:141], v[96:111]
	v_add_f32_e32 v84, v80, v84
	v_exp_f32_e32 v75, v86
	v_add_f32_e32 v84, v73, v84
	v_exp_f32_e32 v83, v87
	v_add_f32_e32 v84, v81, v84
	v_exp_f32_e32 v76, v88
	v_add_f32_e32 v84, v74, v84
	v_mfma_f32_32x32x16_bf16 v[96:111], v[162:165], v[112:115], v[96:111]
	v_exp_f32_e32 v85, v89
	v_add_f32_e32 v84, v82, v84
	v_exp_f32_e32 v77, v90
	v_add_f32_e32 v84, v75, v84
	v_exp_f32_e32 v87, v91
	v_add_f32_e32 v84, v83, v84
	v_exp_f32_e32 v78, v92
	v_mfma_f32_32x32x16_bf16 v[96:111], v[166:169], v[116:119], v[96:111]
	v_add_f32_e32 v84, v76, v84
	v_exp_f32_e32 v89, v93
	v_add_f32_e32 v84, v85, v84
	v_exp_f32_e32 v79, v94
	v_add_f32_e32 v84, v77, v84
	v_exp_f32_e32 v90, v95
	v_add_f32_e32 v84, v87, v84
	v_mfma_f32_32x32x16_bf16 v[96:111], v[174:177], v[120:123], v[96:111]
	v_add_f32_e32 v84, v78, v84
	v_add_f32_e32 v84, v89, v84
	v_add_f32_e32 v84, v79, v84
	v_add_f32_e32 v84, v90, v84
	v_lshl_add_u32 v88, v247, 2, s2
	v_cvt_pk_bf16_f32 v72, v72, v80
	v_cvt_pk_bf16_f32 v73, v73, v81
	v_mfma_f32_32x32x16_bf16 v[96:111], v[178:181], v[124:127], v[96:111]
	v_cvt_pk_bf16_f32 v74, v74, v82
	v_cvt_pk_bf16_f32 v75, v75, v83
	v_cvt_pk_bf16_f32 v76, v76, v85
	v_cvt_pk_bf16_f32 v77, v77, v87
	v_cvt_pk_bf16_f32 v78, v78, v89
	v_cvt_pk_bf16_f32 v79, v79, v90
	s_nop 0
	v_permlane32_swap_b32_e32 v72, v74
	v_mfma_f32_32x32x16_bf16 v[96:111], v[182:185], v[130:133], v[96:111]
	v_permlane32_swap_b32_e32 v73, v75
	v_permlane32_swap_b32_e32 v76, v78
	v_permlane32_swap_b32_e32 v77, v79
	v_mfma_f32_32x32x16_bf16 v[96:111], v[186:189], v[134:137], v[96:111]
	s_nop 11
	v_exp_f32_e32 v91, v96
	v_exp_f32_e32 v92, v97
	v_exp_f32_e32 v93, v98
	v_exp_f32_e32 v94, v99
	v_exp_f32_e32 v95, v100
	v_add_f32_e32 v84, v84, v91
	v_exp_f32_e32 v96, v101
	v_add_f32_e32 v84, v92, v84
	v_exp_f32_e32 v97, v102
	v_add_f32_e32 v84, v93, v84
	v_exp_f32_e32 v98, v103
	v_add_f32_e32 v84, v94, v84
	v_exp_f32_e32 v99, v104
	v_add_f32_e32 v84, v95, v84
	v_exp_f32_e32 v100, v105
	v_add_f32_e32 v84, v96, v84
	v_exp_f32_e32 v101, v106
	v_add_f32_e32 v84, v97, v84
	v_exp_f32_e32 v102, v107
	v_add_f32_e32 v84, v98, v84
	v_exp_f32_e32 v103, v108
	v_add_f32_e32 v84, v99, v84
	v_exp_f32_e32 v104, v109
	v_add_f32_e32 v84, v100, v84
	v_exp_f32_e32 v105, v110
	v_add_f32_e32 v84, v101, v84
	v_exp_f32_e32 v106, v111
	v_add_f32_e32 v84, v102, v84
	v_add_f32_e32 v84, v103, v84
	v_add_f32_e32 v84, v104, v84
	v_add_f32_e32 v84, v105, v84
	v_add_f32_e32 v84, v106, v84
	v_mov_b32_e32 v86, v84
	s_nop 1
	v_permlane32_swap_b32_e32 v84, v86
	v_cvt_pk_bf16_f32 v80, v91, v92
	v_cvt_pk_bf16_f32 v81, v93, v94
	v_cvt_pk_bf16_f32 v82, v95, v96
	v_cvt_pk_bf16_f32 v83, v97, v98
	v_cvt_pk_bf16_f32 v90, v99, v100
	v_cvt_pk_bf16_f32 v91, v101, v102
	v_cvt_pk_bf16_f32 v92, v103, v104
	v_cvt_pk_bf16_f32 v93, v105, v106
	s_nop 0
	v_permlane32_swap_b32_e32 v80, v82
	v_permlane32_swap_b32_e32 v81, v83
	v_permlane32_swap_b32_e32 v90, v92
	v_permlane32_swap_b32_e32 v91, v93
	ds_read_b64_tr_b16 v[94:95], v206 offset:0x4000
	ds_read_b64_tr_b16 v[96:97], v206 offset:0x4800
	ds_read_b64_tr_b16 v[98:99], v206 offset:0x5000
	ds_read_b64_tr_b16 v[100:101], v206 offset:0x5800
	ds_read_b64_tr_b16 v[102:103], v206 offset:0x6000
	ds_read_b64_tr_b16 v[104:105], v206 offset:0x6800
	ds_read_b64_tr_b16 v[106:107], v206 offset:0x7000
	ds_read_b64_tr_b16 v[108:109], v206 offset:0x7800
	s_waitcnt lgkmcnt(0)
; #define SBAR() __builtin_amdgcn_sched_barrier(0)
; __device__ __forceinline__ int crow(int r, int hi) { return (r & 3) + 8 * (r >> 2) + 4 * hi; }
; #define NOP_() do { } while (0)
; template <bool PARTIAL, bool FIXED> ...
;     ...
;   HALF_A(2, 1, do { if (mask_last) { asm volatile("; masked tail tile" ::: "memory"); const float NEG = -INFINITY; \
;       _Pragma("unroll") for (int r = 8; r < 16; ++r) pA0[r] = NEG; _Pragma("unroll") for (int r = 0; r < 16; ++r) pA1[r] = NEG; } } while (0), NOP_(), NOP_());
;     ...
;   SBAR(); finishSM(pA0, pA1, alA, l_reg, pa0, pa1, pa2, pa3); SBAR();
;   pv_i<2 * 16384>(o, vbi, pa0, pa1, pa2, pa3);
;     ...
;   if (PARTIAL) {
;     if (wid < 2) { float* po = PO + (wid * QBLK) * 128;
; #pragma unroll
;       for (int r = 0; r < 16; ++r) { const int orow = crow(r, hi);
; #pragma unroll
;         for (int d0 = 0; d0 < 4; ++d0) po[orow * 128 + d0 * 32 + r32] = o[d0][r]; }
;       if (hi == 0) { PO[8192 + (wid * QBLK + r32) * 2] = m_reg; PO[8192 + (wid * QBLK + r32) * 2 + 1] = l_reg; } }
;     __syncthreads();
;     return;
;   }
;   if (hi == 0) li_l[r32] = l_reg; asm volatile("s_waitcnt lgkmcnt(0)" ::: "memory");
	s_nop 0
	v_mfma_f32_32x32x16_bf16 v[0:15], v[72:75], v[94:97], v[0:15]
	ds_read_b64_tr_b16 v[94:95], v206 offset:0x4200
	ds_read_b64_tr_b16 v[96:97], v206 offset:0x4a00
	v_mfma_f32_32x32x16_bf16 v[0:15], v[76:79], v[98:101], v[0:15]
	ds_read_b64_tr_b16 v[98:99], v206 offset:0x5200
	ds_read_b64_tr_b16 v[100:101], v206 offset:0x5a00
	v_mfma_f32_32x32x16_bf16 v[0:15], v[80:83], v[102:105], v[0:15]
	ds_read_b64_tr_b16 v[102:103], v206 offset:0x6200
	ds_read_b64_tr_b16 v[104:105], v206 offset:0x6a00
	v_mfma_f32_32x32x16_bf16 v[0:15], v[90:93], v[106:109], v[0:15]
	ds_read_b64_tr_b16 v[106:107], v206 offset:0x7200
	ds_read_b64_tr_b16 v[108:109], v206 offset:0x7a00
	s_waitcnt lgkmcnt(0)
	v_mfma_f32_32x32x16_bf16 v[16:31], v[72:75], v[94:97], v[16:31]
	ds_read_b64_tr_b16 v[94:95], v206 offset:0x4400
	ds_read_b64_tr_b16 v[96:97], v206 offset:0x4c00
	v_mfma_f32_32x32x16_bf16 v[16:31], v[76:79], v[98:101], v[16:31]
	ds_read_b64_tr_b16 v[98:99], v206 offset:0x5400
	ds_read_b64_tr_b16 v[100:101], v206 offset:0x5c00
	v_mfma_f32_32x32x16_bf16 v[16:31], v[80:83], v[102:105], v[16:31]
	ds_read_b64_tr_b16 v[102:103], v206 offset:0x6400
	ds_read_b64_tr_b16 v[104:105], v206 offset:0x6c00
	v_mfma_f32_32x32x16_bf16 v[16:31], v[90:93], v[106:109], v[16:31]
	ds_read_b64_tr_b16 v[106:107], v206 offset:0x7400
	ds_read_b64_tr_b16 v[108:109], v206 offset:0x7c00
	s_waitcnt lgkmcnt(0)
	v_mfma_f32_32x32x16_bf16 v[32:47], v[72:75], v[94:97], v[32:47]
	ds_read_b64_tr_b16 v[94:95], v206 offset:0x4600
	ds_read_b64_tr_b16 v[96:97], v206 offset:0x4e00
	v_mfma_f32_32x32x16_bf16 v[32:47], v[76:79], v[98:101], v[32:47]
	ds_read_b64_tr_b16 v[98:99], v206 offset:0x5600
	ds_read_b64_tr_b16 v[100:101], v206 offset:0x5e00
	v_mfma_f32_32x32x16_bf16 v[32:47], v[80:83], v[102:105], v[32:47]
	ds_read_b64_tr_b16 v[102:103], v206 offset:0x6600
	ds_read_b64_tr_b16 v[104:105], v206 offset:0x6e00
	v_mfma_f32_32x32x16_bf16 v[32:47], v[90:93], v[106:109], v[32:47]
	ds_read_b64_tr_b16 v[106:107], v206 offset:0x7600
	ds_read_b64_tr_b16 v[108:109], v206 offset:0x7e00
	s_waitcnt lgkmcnt(0)
	v_mfma_f32_32x32x16_bf16 v[48:63], v[72:75], v[94:97], v[48:63]
	v_exp_f32_e32 v64, v64
	v_exp_f32_e32 v65, v65
	v_exp_f32_e32 v66, v66
	v_exp_f32_e32 v67, v67
	v_exp_f32_e32 v68, v68
	v_exp_f32_e32 v69, v69
	v_exp_f32_e32 v70, v70
	v_mfma_f32_32x32x16_bf16 v[48:63], v[76:79], v[98:101], v[48:63]
	v_exp_f32_e32 v71, v71
	v_mfma_f32_32x32x16_bf16 v[48:63], v[80:83], v[102:105], v[48:63]
	v_mfma_f32_32x32x16_bf16 v[48:63], v[90:93], v[106:109], v[48:63]
	v_add_f32_e32 v72, 0, v64
	v_add_f32_e32 v72, v65, v72
	v_add_f32_e32 v72, v66, v72
	v_add_f32_e32 v72, v67, v72
	v_add_f32_e32 v72, v68, v72
	v_add_f32_e32 v72, v69, v72
	v_add_f32_e32 v72, v70, v72
	v_add_f32_e32 v72, v71, v72
	v_add_f32_e32 v85, 0, v72
	v_mov_b32_e32 v87, v85
	s_nop 1
	v_permlane32_swap_b32_e32 v85, v87
	v_cvt_pk_bf16_f32 v64, v64, v65
	v_cvt_pk_bf16_f32 v65, v66, v67
	v_cvt_pk_bf16_f32 v66, v68, v69
	v_cvt_pk_bf16_f32 v67, v70, v71
	v_cvt_pk_bf16_f32 v68, v129, v129
	v_cvt_pk_bf16_f32 v69, v129, v129
	v_cvt_pk_bf16_f32 v70, v129, v129
	v_cvt_pk_bf16_f32 v71, v129, v129
	v_cvt_pk_bf16_f32 v72, v129, v129
	v_cvt_pk_bf16_f32 v73, v129, v129
	v_cvt_pk_bf16_f32 v74, v129, v129
	v_cvt_pk_bf16_f32 v75, v129, v129
	v_cvt_pk_bf16_f32 v76, v129, v129
	v_cvt_pk_bf16_f32 v77, v129, v129
	v_cvt_pk_bf16_f32 v78, v129, v129
	v_cvt_pk_bf16_f32 v79, v129, v129
	s_nop 0
	v_permlane32_swap_b32_e32 v64, v66
	v_permlane32_swap_b32_e32 v65, v67
	v_permlane32_swap_b32_e32 v68, v70
	v_permlane32_swap_b32_e32 v69, v71
	v_permlane32_swap_b32_e32 v72, v74
	v_permlane32_swap_b32_e32 v73, v75
	v_permlane32_swap_b32_e32 v76, v78
	v_permlane32_swap_b32_e32 v77, v79
	ds_read_b64_tr_b16 v[80:81], v206 offset:0x8000
	ds_read_b64_tr_b16 v[82:83], v206 offset:0x8800
	ds_read_b64_tr_b16 v[90:91], v206 offset:0x9000
	ds_read_b64_tr_b16 v[92:93], v206 offset:0x9800
	ds_read_b64_tr_b16 v[94:95], v206 offset:0xa000
	ds_read_b64_tr_b16 v[96:97], v206 offset:0xa800
	ds_read_b64_tr_b16 v[98:99], v206 offset:0xb000
	ds_read_b64_tr_b16 v[100:101], v206 offset:0xb800
	s_waitcnt lgkmcnt(0)
	s_nop 0
	v_mfma_f32_32x32x16_bf16 v[0:15], v[64:67], v[80:83], v[0:15]
	ds_read_b64_tr_b16 v[80:81], v206 offset:0x8200
	ds_read_b64_tr_b16 v[82:83], v206 offset:0x8a00
	v_mfma_f32_32x32x16_bf16 v[0:15], v[68:71], v[90:93], v[0:15]
	ds_read_b64_tr_b16 v[90:91], v206 offset:0x9200
	ds_read_b64_tr_b16 v[92:93], v206 offset:0x9a00
	v_mfma_f32_32x32x16_bf16 v[0:15], v[72:75], v[94:97], v[0:15]
	ds_read_b64_tr_b16 v[94:95], v206 offset:0xa200
	ds_read_b64_tr_b16 v[96:97], v206 offset:0xaa00
	v_mfma_f32_32x32x16_bf16 v[0:15], v[76:79], v[98:101], v[0:15]
	ds_read_b64_tr_b16 v[98:99], v206 offset:0xb200
	ds_read_b64_tr_b16 v[100:101], v206 offset:0xba00
	s_waitcnt lgkmcnt(0)
	v_mfma_f32_32x32x16_bf16 v[16:31], v[64:67], v[80:83], v[16:31]
	ds_read_b64_tr_b16 v[80:81], v206 offset:0x8400
	ds_read_b64_tr_b16 v[82:83], v206 offset:0x8c00
	v_mfma_f32_32x32x16_bf16 v[16:31], v[68:71], v[90:93], v[16:31]
	ds_read_b64_tr_b16 v[90:91], v206 offset:0x9400
	ds_read_b64_tr_b16 v[92:93], v206 offset:0x9c00
	v_mfma_f32_32x32x16_bf16 v[16:31], v[72:75], v[94:97], v[16:31]
	ds_read_b64_tr_b16 v[94:95], v206 offset:0xa400
	ds_read_b64_tr_b16 v[96:97], v206 offset:0xac00
	v_mfma_f32_32x32x16_bf16 v[16:31], v[76:79], v[98:101], v[16:31]
	ds_read_b64_tr_b16 v[98:99], v206 offset:0xb400
	ds_read_b64_tr_b16 v[100:101], v206 offset:0xbc00
	s_waitcnt lgkmcnt(0)
	v_mfma_f32_32x32x16_bf16 v[32:47], v[64:67], v[80:83], v[32:47]
	ds_read_b64_tr_b16 v[80:81], v206 offset:0x8600
	ds_read_b64_tr_b16 v[82:83], v206 offset:0x8e00
	v_mfma_f32_32x32x16_bf16 v[32:47], v[68:71], v[90:93], v[32:47]
	ds_read_b64_tr_b16 v[90:91], v206 offset:0x9600
	ds_read_b64_tr_b16 v[92:93], v206 offset:0x9e00
	v_mfma_f32_32x32x16_bf16 v[32:47], v[72:75], v[94:97], v[32:47]
	ds_read_b64_tr_b16 v[94:95], v206 offset:0xa600
	ds_read_b64_tr_b16 v[96:97], v206 offset:0xae00
	v_mfma_f32_32x32x16_bf16 v[32:47], v[76:79], v[98:101], v[32:47]
	ds_read_b64_tr_b16 v[98:99], v206 offset:0xb600
	ds_read_b64_tr_b16 v[100:101], v206 offset:0xbe00
	s_waitcnt lgkmcnt(0)
	v_mfma_f32_32x32x16_bf16 v[48:63], v[64:67], v[80:83], v[48:63]
	v_cmp_gt_u32_e32 vcc, 32, v190
	v_mfma_f32_32x32x16_bf16 v[48:63], v[68:71], v[90:93], v[48:63]
	v_mfma_f32_32x32x16_bf16 v[48:63], v[72:75], v[94:97], v[48:63]
	v_mfma_f32_32x32x16_bf16 v[48:63], v[76:79], v[98:101], v[48:63]
	s_and_saveexec_b64 s[28:29], vcc
	s_cbranch_execz .LBB0_309
	v_add_f32_e32 v64, v128, v218
	v_add_f32_e32 v66, v215, v64
	v_pk_add_f32 v[64:65], v[84:85], v[86:87]
	v_lshl_add_u32 v67, v192, 2, v88
	v_add_f32_e32 v64, v66, v64
	v_add_f32_e32 v64, v64, v65
	ds_write_b32 v67, v64
	s_branch .LBB0_309
